# E4 pass 1: the 54 per-row bf16 loads of a half issued up front (one wait instead of ~22 serialized round trips)
# speedup vs baseline: 1.0388x; 1.0083x over previous
.LBB0_661:
	s_or_b64 exec, exec, s[4:5]
	v_mov_b32_e32 v151, v197
	v_mov_b32_e32 v153, v197
	v_add_u32_e32 v135, -1, v170
	v_cmp_le_i32_e64 s[98:99], s60, v135
	v_cmp_gt_i32_e64 s[100:101], s23, v135
	s_and_b64 s[98:99], s[98:99], s[100:101]
	v_cndmask_b32_e64 v135, v170, v135, s[98:99]
	v_mul_lo_u32 v134, v135, s70
	v_add_u32_e32 v136, v134, v196
	global_load_ushort v80, v136, s[44:45]
	v_add_u32_e32 v136, v134, v150
	global_load_ushort v81, v136, s[44:45]
	v_add_u32_e32 v136, v134, v152
	global_load_ushort v82, v136, s[44:45]
	v_mul_lo_u32 v134, v170, s70
	v_add_u32_e32 v136, v134, v196
	global_load_ushort v83, v136, s[44:45]
	v_add_u32_e32 v136, v134, v150
	global_load_ushort v84, v136, s[44:45]
	v_add_u32_e32 v136, v134, v152
	global_load_ushort v85, v136, s[44:45]
	v_add_u32_e32 v135, 1, v170
	v_cmp_le_i32_e64 s[98:99], s60, v135
	v_cmp_gt_i32_e64 s[100:101], s23, v135
	s_and_b64 s[98:99], s[98:99], s[100:101]
	v_cndmask_b32_e64 v135, v170, v135, s[98:99]
	v_mul_lo_u32 v134, v135, s70
	v_add_u32_e32 v136, v134, v196
	global_load_ushort v86, v136, s[44:45]
	v_add_u32_e32 v136, v134, v150
	global_load_ushort v87, v136, s[44:45]
	v_add_u32_e32 v136, v134, v152
	global_load_ushort v88, v136, s[44:45]
	v_add_u32_e32 v135, 2, v170
	v_cmp_le_i32_e64 s[98:99], s60, v135
	v_cmp_gt_i32_e64 s[100:101], s23, v135
	s_and_b64 s[98:99], s[98:99], s[100:101]
	v_cndmask_b32_e64 v135, v170, v135, s[98:99]
	v_mul_lo_u32 v134, v135, s70
	v_add_u32_e32 v136, v134, v196
	global_load_ushort v89, v136, s[44:45]
	v_add_u32_e32 v136, v134, v150
	global_load_ushort v90, v136, s[44:45]
	v_add_u32_e32 v136, v134, v152
	global_load_ushort v91, v136, s[44:45]
	v_add_u32_e32 v135, 3, v170
	v_cmp_le_i32_e64 s[98:99], s60, v135
	v_cmp_gt_i32_e64 s[100:101], s23, v135
	s_and_b64 s[98:99], s[98:99], s[100:101]
	v_cndmask_b32_e64 v135, v170, v135, s[98:99]
	v_mul_lo_u32 v134, v135, s70
	v_add_u32_e32 v136, v134, v196
	global_load_ushort v92, v136, s[44:45]
	v_add_u32_e32 v136, v134, v150
	global_load_ushort v93, v136, s[44:45]
	v_add_u32_e32 v136, v134, v152
	global_load_ushort v94, v136, s[44:45]
	v_add_u32_e32 v135, 4, v170
	v_cmp_le_i32_e64 s[98:99], s60, v135
	v_cmp_gt_i32_e64 s[100:101], s23, v135
	s_and_b64 s[98:99], s[98:99], s[100:101]
	v_cndmask_b32_e64 v135, v170, v135, s[98:99]
	v_mul_lo_u32 v134, v135, s70
	v_add_u32_e32 v136, v134, v196
	global_load_ushort v95, v136, s[44:45]
	v_add_u32_e32 v136, v134, v150
	global_load_ushort v96, v136, s[44:45]
	v_add_u32_e32 v136, v134, v152
	global_load_ushort v97, v136, s[44:45]
	v_add_u32_e32 v135, 5, v170
	v_cmp_le_i32_e64 s[98:99], s60, v135
	v_cmp_gt_i32_e64 s[100:101], s23, v135
	s_and_b64 s[98:99], s[98:99], s[100:101]
	v_cndmask_b32_e64 v135, v170, v135, s[98:99]
	v_mul_lo_u32 v134, v135, s70
	v_add_u32_e32 v136, v134, v196
	global_load_ushort v98, v136, s[44:45]
	v_add_u32_e32 v136, v134, v150
	global_load_ushort v99, v136, s[44:45]
	v_add_u32_e32 v136, v134, v152
	global_load_ushort v100, v136, s[44:45]
	v_add_u32_e32 v135, 6, v170
	v_cmp_le_i32_e64 s[98:99], s60, v135
	v_cmp_gt_i32_e64 s[100:101], s23, v135
	s_and_b64 s[98:99], s[98:99], s[100:101]
	v_cndmask_b32_e64 v135, v170, v135, s[98:99]
	v_mul_lo_u32 v134, v135, s70
	v_add_u32_e32 v136, v134, v196
	global_load_ushort v101, v136, s[44:45]
	v_add_u32_e32 v136, v134, v150
	global_load_ushort v102, v136, s[44:45]
	v_add_u32_e32 v136, v134, v152
	global_load_ushort v103, v136, s[44:45]
	v_add_u32_e32 v135, 7, v170
	v_cmp_le_i32_e64 s[98:99], s60, v135
	v_cmp_gt_i32_e64 s[100:101], s23, v135
	s_and_b64 s[98:99], s[98:99], s[100:101]
	v_cndmask_b32_e64 v135, v170, v135, s[98:99]
	v_mul_lo_u32 v134, v135, s70
	v_add_u32_e32 v136, v134, v196
	global_load_ushort v104, v136, s[44:45]
	v_add_u32_e32 v136, v134, v150
	global_load_ushort v105, v136, s[44:45]
	v_add_u32_e32 v136, v134, v152
	global_load_ushort v106, v136, s[44:45]
	v_add_u32_e32 v135, 8, v170
	v_cmp_le_i32_e64 s[98:99], s60, v135
	v_cmp_gt_i32_e64 s[100:101], s23, v135
	s_and_b64 s[98:99], s[98:99], s[100:101]
	v_cndmask_b32_e64 v135, v170, v135, s[98:99]
	v_mul_lo_u32 v134, v135, s70
	v_add_u32_e32 v136, v134, v196
	global_load_ushort v107, v136, s[44:45]
	v_add_u32_e32 v136, v134, v150
	global_load_ushort v108, v136, s[44:45]
	v_add_u32_e32 v136, v134, v152
	global_load_ushort v109, v136, s[44:45]
	v_add_u32_e32 v135, 9, v170
	v_cmp_le_i32_e64 s[98:99], s60, v135
	v_cmp_gt_i32_e64 s[100:101], s23, v135
	s_and_b64 s[98:99], s[98:99], s[100:101]
	v_cndmask_b32_e64 v135, v170, v135, s[98:99]
	v_mul_lo_u32 v134, v135, s70
	v_add_u32_e32 v136, v134, v196
	global_load_ushort v110, v136, s[44:45]
	v_add_u32_e32 v136, v134, v150
	global_load_ushort v111, v136, s[44:45]
	v_add_u32_e32 v136, v134, v152
	global_load_ushort v112, v136, s[44:45]
	v_add_u32_e32 v135, 10, v170
	v_cmp_le_i32_e64 s[98:99], s60, v135
	v_cmp_gt_i32_e64 s[100:101], s23, v135
	s_and_b64 s[98:99], s[98:99], s[100:101]
	v_cndmask_b32_e64 v135, v170, v135, s[98:99]
	v_mul_lo_u32 v134, v135, s70
	v_add_u32_e32 v136, v134, v196
	global_load_ushort v113, v136, s[44:45]
	v_add_u32_e32 v136, v134, v150
	global_load_ushort v114, v136, s[44:45]
	v_add_u32_e32 v136, v134, v152
	global_load_ushort v115, v136, s[44:45]
	v_add_u32_e32 v135, 11, v170
	v_cmp_le_i32_e64 s[98:99], s60, v135
	v_cmp_gt_i32_e64 s[100:101], s23, v135
	s_and_b64 s[98:99], s[98:99], s[100:101]
	v_cndmask_b32_e64 v135, v170, v135, s[98:99]
	v_mul_lo_u32 v134, v135, s70
	v_add_u32_e32 v136, v134, v196
	global_load_ushort v116, v136, s[44:45]
	v_add_u32_e32 v136, v134, v150
	global_load_ushort v117, v136, s[44:45]
	v_add_u32_e32 v136, v134, v152
	global_load_ushort v118, v136, s[44:45]
	v_add_u32_e32 v135, 12, v170
	v_cmp_le_i32_e64 s[98:99], s60, v135
	v_cmp_gt_i32_e64 s[100:101], s23, v135
	s_and_b64 s[98:99], s[98:99], s[100:101]
	v_cndmask_b32_e64 v135, v170, v135, s[98:99]
	v_mul_lo_u32 v134, v135, s70
	v_add_u32_e32 v136, v134, v196
	global_load_ushort v119, v136, s[44:45]
	v_add_u32_e32 v136, v134, v150
	global_load_ushort v120, v136, s[44:45]
	v_add_u32_e32 v136, v134, v152
	global_load_ushort v121, v136, s[44:45]
	v_add_u32_e32 v135, 13, v170
	v_cmp_le_i32_e64 s[98:99], s60, v135
	v_cmp_gt_i32_e64 s[100:101], s23, v135
	s_and_b64 s[98:99], s[98:99], s[100:101]
	v_cndmask_b32_e64 v135, v170, v135, s[98:99]
	v_mul_lo_u32 v134, v135, s70
	v_add_u32_e32 v136, v134, v196
	global_load_ushort v122, v136, s[44:45]
	v_add_u32_e32 v136, v134, v150
	global_load_ushort v123, v136, s[44:45]
	v_add_u32_e32 v136, v134, v152
	global_load_ushort v124, v136, s[44:45]
	v_add_u32_e32 v135, 14, v170
	v_cmp_le_i32_e64 s[98:99], s60, v135
	v_cmp_gt_i32_e64 s[100:101], s23, v135
	s_and_b64 s[98:99], s[98:99], s[100:101]
	v_cndmask_b32_e64 v135, v170, v135, s[98:99]
	v_mul_lo_u32 v134, v135, s70
	v_add_u32_e32 v136, v134, v196
	global_load_ushort v125, v136, s[44:45]
	v_add_u32_e32 v136, v134, v150
	global_load_ushort v126, v136, s[44:45]
	v_add_u32_e32 v136, v134, v152
	global_load_ushort v127, v136, s[44:45]
	v_add_u32_e32 v135, 15, v170
	v_cmp_le_i32_e64 s[98:99], s60, v135
	v_cmp_gt_i32_e64 s[100:101], s23, v135
	s_and_b64 s[98:99], s[98:99], s[100:101]
	v_cndmask_b32_e64 v135, v170, v135, s[98:99]
	v_mul_lo_u32 v134, v135, s70
	v_add_u32_e32 v136, v134, v196
	global_load_ushort v128, v136, s[44:45]
	v_add_u32_e32 v136, v134, v150
	global_load_ushort v129, v136, s[44:45]
	v_add_u32_e32 v136, v134, v152
	global_load_ushort v130, v136, s[44:45]
	v_add_u32_e32 v135, 16, v170
	v_cmp_le_i32_e64 s[98:99], s60, v135
	v_cmp_gt_i32_e64 s[100:101], s23, v135
	s_and_b64 s[98:99], s[98:99], s[100:101]
	v_cndmask_b32_e64 v135, v170, v135, s[98:99]
	v_mul_lo_u32 v134, v135, s70
	v_add_u32_e32 v136, v134, v196
	global_load_ushort v131, v136, s[44:45]
	v_add_u32_e32 v136, v134, v150
	global_load_ushort v132, v136, s[44:45]
	v_add_u32_e32 v136, v134, v152
	global_load_ushort v133, v136, s[44:45]
	s_waitcnt vmcnt(0)
	v_cmp_lt_i32_e32 vcc, s60, v170
	v_cmp_ge_i32_e64 s[4:5], s23, v170
	s_and_b64 vcc, vcc, s[4:5]
	v_subbrev_co_u32_e64 v2, s[4:5], 0, v170, vcc
	v_mov_b64_e32 v[0:1], s[44:45]
	v_mad_i64_i32 v[2:3], s[2:3], v2, s70, v[0:1]
	v_lshl_add_u64 v[4:5], v[2:3], 0, v[196:197]
	v_mov_b32_e32 v151, v197
	v_mov_b32_e32 v153, v197
	v_cmp_gt_i32_e64 s[4:5], s23, v170
	v_or_b32_e32 v20, 1, v170
	v_or_b32_e32 v18, 2, v170
	v_or_b32_e32 v24, 3, v170
	v_or_b32_e32 v30, 5, v170
	v_or_b32_e32 v38, 11, v170
	v_or_b32_e32 v36, 12, v170
	v_readlane_b32 s42, v33, 0
	v_ashrrev_i32_e32 v171, 31, v170
	v_readlane_b32 s43, v33, 1
	s_mov_b32 s50, 16
	v_lshlrev_b32_e32 v6, 16, v80
	v_lshl_add_u64 v[4:5], v[2:3], 0, v[150:151]
	v_lshl_add_u64 v[2:3], v[2:3], 0, v[152:153]
	v_cndmask_b32_e32 v6, 0, v6, vcc
	v_lshlrev_b32_e32 v4, 16, v81
	v_cndmask_b32_e32 v7, 0, v4, vcc
	v_lshlrev_b32_e32 v2, 16, v82
	v_cndmask_b32_e32 v8, 0, v2, vcc
	v_mad_i64_i32 v[2:3], s[2:3], v170, s70, v[0:1]
	v_lshl_add_u64 v[4:5], v[2:3], 0, v[196:197]
	v_cmp_le_i32_e32 vcc, s60, v170
	s_and_b64 vcc, vcc, s[4:5]
	v_cmp_gt_i32_e64 s[4:5], s23, v20
	v_lshlrev_b32_e32 v9, 16, v83
	v_lshl_add_u64 v[4:5], v[2:3], 0, v[150:151]
	v_lshl_add_u64 v[2:3], v[2:3], 0, v[152:153]
	v_cndmask_b32_e32 v15, 0, v9, vcc
	v_lshlrev_b32_e32 v4, 16, v84
	v_cndmask_b32_e32 v16, 0, v4, vcc
	v_lshlrev_b32_e32 v2, 16, v85
	v_cndmask_b32_e32 v17, 0, v2, vcc
	v_cmp_le_i32_e32 vcc, s60, v20
	s_and_b64 vcc, vcc, s[4:5]
	v_cmp_gt_i32_e64 s[4:5], s23, v18
	v_cndmask_b32_e32 v2, v170, v20, vcc
	v_mad_i64_i32 v[2:3], s[2:3], v2, s70, v[0:1]
	v_lshl_add_u64 v[4:5], v[2:3], 0, v[196:197]
	v_lshlrev_b32_e32 v9, 16, v86
	v_lshl_add_u64 v[4:5], v[2:3], 0, v[150:151]
	v_lshl_add_u64 v[2:3], v[2:3], 0, v[152:153]
	v_cndmask_b32_e32 v14, 0, v9, vcc
	v_lshlrev_b32_e32 v4, 16, v87
	v_cndmask_b32_e32 v12, 0, v4, vcc
	v_lshlrev_b32_e32 v2, 16, v88
	v_cndmask_b32_e32 v10, 0, v2, vcc
	v_cmp_le_i32_e32 vcc, s60, v18
	s_and_b64 vcc, vcc, s[4:5]
	v_cmp_gt_i32_e64 s[4:5], s23, v24
	v_cndmask_b32_e32 v2, v170, v18, vcc
	v_mad_i64_i32 v[2:3], s[2:3], v2, s70, v[0:1]
	v_lshl_add_u64 v[4:5], v[2:3], 0, v[196:197]
	v_lshlrev_b32_e32 v9, 16, v89
	v_lshl_add_u64 v[4:5], v[2:3], 0, v[150:151]
	v_lshl_add_u64 v[2:3], v[2:3], 0, v[152:153]
	v_lshlrev_b32_e32 v5, 16, v90
	v_cndmask_b32_e32 v3, 0, v5, vcc
	v_sub_f32_e32 v5, v6, v15
	v_fma_f32 v5, v141, v5, v15
	v_sub_f32_e32 v6, v14, v15
	v_fmac_f32_e32 v5, v185, v6
	v_sub_f32_e32 v6, v7, v16
	v_fma_f32 v6, v189, v6, v16
	v_sub_f32_e32 v7, v12, v16
	v_mul_f32_e32 v5, 0xbfb8aa3b, v5
	v_fmac_f32_e32 v6, v186, v7
	v_exp_f32_e32 v5, v5
	v_mul_f32_e32 v6, 0xbfb8aa3b, v6
	v_exp_f32_e32 v6, v6
	v_lshlrev_b32_e32 v2, 16, v91
	v_add_f32_e32 v5, 1.0, v5
	v_rcp_f32_e32 v5, v5
	v_add_f32_e32 v6, 1.0, v6
	v_rcp_f32_e32 v6, v6
	v_cndmask_b32_e32 v4, 0, v9, vcc
	v_cndmask_b32_e32 v2, 0, v2, vcc
	v_cvt_pk_bf16_f32 v5, v5, s0
	v_cmp_le_i32_e32 vcc, s60, v24
	v_sub_f32_e32 v7, v8, v17
	ds_write_b16 v194, v5 offset:34816
	v_cvt_pk_bf16_f32 v5, v6, s0
	s_and_b64 vcc, vcc, s[4:5]
	v_fma_f32 v13, v187, v7, v17
	v_sub_f32_e32 v7, v10, v17
	ds_write_b16 v194, v5 offset:34944
	v_cndmask_b32_e32 v5, v170, v24, vcc
	v_fmac_f32_e32 v13, v188, v7
	v_mad_i64_i32 v[6:7], s[2:3], v5, s70, v[0:1]
	v_lshl_add_u64 v[8:9], v[6:7], 0, v[196:197]
	v_lshl_add_u64 v[8:9], v[6:7], 0, v[150:151]
	v_lshl_add_u64 v[6:7], v[6:7], 0, v[152:153]
	v_sub_f32_e32 v7, v4, v14
	v_lshlrev_b32_e32 v5, 16, v92
	v_cndmask_b32_e32 v11, 0, v5, vcc
	v_sub_f32_e32 v5, v15, v14
	v_fma_f32 v5, v141, v5, v14
	v_lshlrev_b32_e32 v8, 16, v93
	v_fmac_f32_e32 v5, v185, v7
	v_sub_f32_e32 v7, v16, v12
	v_cndmask_b32_e32 v9, 0, v8, vcc
	v_fma_f32 v7, v189, v7, v12
	v_sub_f32_e32 v8, v3, v12
	v_mul_f32_e32 v5, 0xbfb8aa3b, v5
	v_fmac_f32_e32 v7, v186, v8
	v_exp_f32_e32 v5, v5
	v_mul_f32_e32 v7, 0xbfb8aa3b, v7
	v_exp_f32_e32 v7, v7
	v_lshlrev_b32_e32 v6, 16, v94
	v_add_f32_e32 v5, 1.0, v5
	v_rcp_f32_e32 v5, v5
	v_add_f32_e32 v7, 1.0, v7
	v_rcp_f32_e32 v7, v7
	v_or_b32_e32 v16, 4, v170
	v_cndmask_b32_e32 v6, 0, v6, vcc
	v_cvt_pk_bf16_f32 v5, v5, s0
	v_cmp_le_i32_e32 vcc, s60, v16
	v_cmp_gt_i32_e64 s[4:5], s23, v16
	ds_write_b16 v194, v5 offset:35104
	v_cvt_pk_bf16_f32 v5, v7, s0
	s_and_b64 vcc, vcc, s[4:5]
	ds_write_b16 v194, v5 offset:35232
	v_cndmask_b32_e32 v5, v170, v16, vcc
	v_mad_i64_i32 v[22:23], s[2:3], v5, s70, v[0:1]
	v_sub_f32_e32 v8, v17, v10
	v_lshl_add_u64 v[26:27], v[22:23], 0, v[196:197]
	v_fma_f32 v17, v187, v8, v10
	v_sub_f32_e32 v8, v2, v10
	v_lshl_add_u64 v[26:27], v[22:23], 0, v[150:151]
	v_lshl_add_u64 v[22:23], v[22:23], 0, v[152:153]
	v_fmac_f32_e32 v17, v188, v8
	v_sub_f32_e32 v14, v14, v4
	v_fma_f32 v14, v141, v14, v4
	v_sub_f32_e32 v12, v12, v3
	v_fma_f32 v12, v189, v12, v3
	v_sub_f32_e32 v10, v10, v2
	v_fma_f32 v23, v187, v10, v2
	v_sub_f32_e32 v10, v6, v2
	v_fmac_f32_e32 v23, v188, v10
	v_cmp_gt_i32_e64 s[4:5], s23, v30
	v_sub_f32_e32 v2, v2, v6
	v_fma_f32 v25, v187, v2, v6
	v_or_b32_e32 v22, 8, v170
	v_lshlrev_b32_e32 v5, 16, v95
	v_lshlrev_b32_e32 v7, 16, v96
	v_lshlrev_b32_e32 v15, 16, v97
	v_cndmask_b32_e32 v8, 0, v5, vcc
	v_cndmask_b32_e32 v5, 0, v15, vcc
	v_sub_f32_e32 v15, v11, v4
	v_fmac_f32_e32 v14, v185, v15
	v_sub_f32_e32 v15, v9, v3
	v_mul_f32_e32 v14, 0xbfb8aa3b, v14
	v_fmac_f32_e32 v12, v186, v15
	v_exp_f32_e32 v14, v14
	v_mul_f32_e32 v12, 0xbfb8aa3b, v12
	v_exp_f32_e32 v12, v12
	v_cndmask_b32_e32 v7, 0, v7, vcc
	v_add_f32_e32 v14, 1.0, v14
	v_rcp_f32_e32 v14, v14
	v_add_f32_e32 v12, 1.0, v12
	v_rcp_f32_e32 v12, v12
	v_cmp_le_i32_e32 vcc, s60, v30
	v_cvt_pk_bf16_f32 v10, v14, s0
	ds_write_b16 v194, v10 offset:35392
	v_cvt_pk_bf16_f32 v10, v12, s0
	s_and_b64 vcc, vcc, s[4:5]
	ds_write_b16 v194, v10 offset:35520
	v_cndmask_b32_e32 v10, v170, v30, vcc
	v_mad_i64_i32 v[14:15], s[2:3], v10, s70, v[0:1]
	v_lshl_add_u64 v[26:27], v[14:15], 0, v[196:197]
	v_lshl_add_u64 v[26:27], v[14:15], 0, v[150:151]
	v_lshl_add_u64 v[14:15], v[14:15], 0, v[152:153]
	v_sub_f32_e32 v4, v4, v11
	v_fma_f32 v4, v141, v4, v11
	v_sub_f32_e32 v3, v3, v9
	v_fma_f32 v3, v189, v3, v9
	v_sub_f32_e32 v2, v5, v6
	v_fmac_f32_e32 v25, v188, v2
	v_sub_f32_e32 v6, v6, v5
	v_fma_f32 v31, v187, v6, v5
	v_lshlrev_b32_e32 v10, 16, v98
	v_cndmask_b32_e32 v26, 0, v10, vcc
	v_lshlrev_b32_e32 v12, 16, v99
	v_cndmask_b32_e32 v15, 0, v12, vcc
	v_sub_f32_e32 v12, v8, v11
	v_fmac_f32_e32 v4, v185, v12
	v_sub_f32_e32 v12, v7, v9
	v_mul_f32_e32 v4, 0xbfb8aa3b, v4
	v_fmac_f32_e32 v3, v186, v12
	v_exp_f32_e32 v4, v4
	v_mul_f32_e32 v3, 0xbfb8aa3b, v3
	v_exp_f32_e32 v3, v3
	v_lshlrev_b32_e32 v14, 16, v100
	v_add_f32_e32 v4, 1.0, v4
	v_rcp_f32_e32 v4, v4
	v_add_f32_e32 v3, 1.0, v3
	v_rcp_f32_e32 v3, v3
	v_or_b32_e32 v12, 6, v170
	v_cndmask_b32_e32 v10, 0, v14, vcc
	v_cvt_pk_bf16_f32 v2, v4, s0
	v_cmp_le_i32_e32 vcc, s60, v12
	v_cmp_gt_i32_e64 s[4:5], s23, v12
	ds_write_b16 v194, v2 offset:35680
	v_cvt_pk_bf16_f32 v2, v3, s0
	s_and_b64 vcc, vcc, s[4:5]
	ds_write_b16 v194, v2 offset:35808
	v_cndmask_b32_e32 v2, v170, v12, vcc
	v_mad_i64_i32 v[2:3], s[2:3], v2, s70, v[0:1]
	v_lshl_add_u64 v[28:29], v[2:3], 0, v[196:197]
	v_lshl_add_u64 v[28:29], v[2:3], 0, v[150:151]
	v_lshl_add_u64 v[2:3], v[2:3], 0, v[152:153]
	v_sub_f32_e32 v11, v11, v8
	v_fma_f32 v11, v141, v11, v8
	v_sub_f32_e32 v9, v9, v7
	v_fma_f32 v9, v189, v9, v7
	v_sub_f32_e32 v6, v10, v5
	v_fmac_f32_e32 v31, v188, v6
	v_sub_f32_e32 v5, v5, v10
	v_fma_f32 v37, v187, v5, v10
	v_lshlrev_b32_e32 v4, 16, v101
	v_cndmask_b32_e32 v4, 0, v4, vcc
	v_lshlrev_b32_e32 v14, 16, v102
	v_cndmask_b32_e32 v3, 0, v14, vcc
	v_sub_f32_e32 v14, v26, v8
	v_fmac_f32_e32 v11, v185, v14
	v_sub_f32_e32 v14, v15, v7
	v_mul_f32_e32 v11, 0xbfb8aa3b, v11
	v_fmac_f32_e32 v9, v186, v14
	v_exp_f32_e32 v11, v11
	v_mul_f32_e32 v9, 0xbfb8aa3b, v9
	v_exp_f32_e32 v9, v9
	v_lshlrev_b32_e32 v2, 16, v103
	v_add_f32_e32 v11, 1.0, v11
	v_rcp_f32_e32 v11, v11
	v_add_f32_e32 v9, 1.0, v9
	v_rcp_f32_e32 v9, v9
	v_or_b32_e32 v14, 7, v170
	v_cndmask_b32_e32 v2, 0, v2, vcc
	v_cvt_pk_bf16_f32 v6, v11, s0
	v_cmp_le_i32_e32 vcc, s60, v14
	v_cmp_gt_i32_e64 s[4:5], s23, v14
	ds_write_b16 v194, v6 offset:35968
	v_cvt_pk_bf16_f32 v6, v9, s0
	s_and_b64 vcc, vcc, s[4:5]
	ds_write_b16 v194, v6 offset:36096
	v_cndmask_b32_e32 v6, v170, v14, vcc
	v_mad_i64_i32 v[28:29], s[2:3], v6, s70, v[0:1]
	v_lshl_add_u64 v[34:35], v[28:29], 0, v[196:197]
	v_lshl_add_u64 v[34:35], v[28:29], 0, v[150:151]
	v_lshl_add_u64 v[28:29], v[28:29], 0, v[152:153]
	v_sub_f32_e32 v8, v8, v26
	v_fma_f32 v8, v141, v8, v26
	v_sub_f32_e32 v7, v7, v15
	v_fma_f32 v7, v189, v7, v15
	v_sub_f32_e32 v5, v2, v10
	v_fmac_f32_e32 v37, v188, v5
	v_cmp_gt_i32_e64 s[4:5], s23, v22
	v_sub_f32_e32 v10, v10, v2
	v_lshlrev_b32_e32 v6, 16, v104
	v_cndmask_b32_e32 v19, 0, v6, vcc
	v_lshlrev_b32_e32 v9, 16, v105
	v_lshlrev_b32_e32 v11, 16, v106
	v_cndmask_b32_e32 v6, 0, v11, vcc
	v_sub_f32_e32 v11, v4, v26
	v_fmac_f32_e32 v8, v185, v11
	v_sub_f32_e32 v11, v3, v15
	v_mul_f32_e32 v8, 0xbfb8aa3b, v8
	v_fmac_f32_e32 v7, v186, v11
	v_exp_f32_e32 v8, v8
	v_mul_f32_e32 v7, 0xbfb8aa3b, v7
	v_exp_f32_e32 v7, v7
	v_cndmask_b32_e32 v9, 0, v9, vcc
	v_add_f32_e32 v8, 1.0, v8
	v_rcp_f32_e32 v8, v8
	v_add_f32_e32 v7, 1.0, v7
	v_rcp_f32_e32 v7, v7
	v_cmp_le_i32_e32 vcc, s60, v22
	v_cvt_pk_bf16_f32 v5, v8, s0
	ds_write_b16 v194, v5 offset:36256
	v_cvt_pk_bf16_f32 v5, v7, s0
	s_and_b64 vcc, vcc, s[4:5]
	ds_write_b16 v194, v5 offset:36384
	v_cndmask_b32_e32 v5, v170, v22, vcc
	v_mad_i64_i32 v[28:29], s[2:3], v5, s70, v[0:1]
	v_lshl_add_u64 v[34:35], v[28:29], 0, v[196:197]
	v_lshl_add_u64 v[34:35], v[28:29], 0, v[150:151]
	v_lshl_add_u64 v[28:29], v[28:29], 0, v[152:153]
	v_or_b32_e32 v28, 9, v170
	v_cmp_gt_i32_e64 s[4:5], s23, v28
	v_lshlrev_b32_e32 v5, 16, v107
	v_cndmask_b32_e32 v21, 0, v5, vcc
	v_lshlrev_b32_e32 v7, 16, v108
	v_sub_f32_e32 v5, v26, v4
	v_cndmask_b32_e32 v11, 0, v7, vcc
	v_fma_f32 v5, v141, v5, v4
	v_sub_f32_e32 v7, v19, v4
	v_fmac_f32_e32 v5, v185, v7
	v_sub_f32_e32 v7, v15, v3
	v_fma_f32 v7, v189, v7, v3
	v_sub_f32_e32 v15, v9, v3
	v_mul_f32_e32 v5, 0xbfb8aa3b, v5
	v_fmac_f32_e32 v7, v186, v15
	v_exp_f32_e32 v5, v5
	v_mul_f32_e32 v7, 0xbfb8aa3b, v7
	v_exp_f32_e32 v7, v7
	v_lshlrev_b32_e32 v8, 16, v109
	v_add_f32_e32 v5, 1.0, v5
	v_rcp_f32_e32 v5, v5
	v_add_f32_e32 v7, 1.0, v7
	v_rcp_f32_e32 v7, v7
	v_cndmask_b32_e32 v8, 0, v8, vcc
	v_cvt_pk_bf16_f32 v5, v5, s0
	v_cmp_le_i32_e32 vcc, s60, v28
	ds_write_b16 v194, v5 offset:36544
	v_cvt_pk_bf16_f32 v5, v7, s0
	s_and_b64 vcc, vcc, s[4:5]
	ds_write_b16 v194, v5 offset:36672
	v_cndmask_b32_e32 v5, v170, v28, vcc
	v_mad_i64_i32 v[26:27], s[2:3], v5, s70, v[0:1]
	v_lshl_add_u64 v[34:35], v[26:27], 0, v[196:197]
	v_fma_f32 v15, v187, v10, v2
	v_sub_f32_e32 v10, v6, v2
	v_lshl_add_u64 v[34:35], v[26:27], 0, v[150:151]
	v_lshl_add_u64 v[26:27], v[26:27], 0, v[152:153]
	v_fmac_f32_e32 v15, v188, v10
	v_sub_f32_e32 v4, v4, v19
	v_fma_f32 v4, v141, v4, v19
	v_sub_f32_e32 v3, v3, v9
	v_fma_f32 v3, v189, v3, v9
	v_sub_f32_e32 v2, v2, v6
	v_fma_f32 v27, v187, v2, v6
	v_sub_f32_e32 v2, v8, v6
	v_or_b32_e32 v34, 10, v170
	v_fmac_f32_e32 v27, v188, v2
	v_cmp_gt_i32_e64 s[4:5], s23, v34
	v_lshlrev_b32_e32 v5, 16, v110
	v_cndmask_b32_e32 v39, 0, v5, vcc
	v_sub_f32_e32 v5, v21, v19
	v_fmac_f32_e32 v4, v185, v5
	v_sub_f32_e32 v5, v11, v9
	v_mul_f32_e32 v4, 0xbfb8aa3b, v4
	v_fmac_f32_e32 v3, v186, v5
	v_exp_f32_e32 v4, v4
	v_mul_f32_e32 v3, 0xbfb8aa3b, v3
	v_exp_f32_e32 v3, v3
	v_lshlrev_b32_e32 v7, 16, v111
	v_add_f32_e32 v4, 1.0, v4
	v_rcp_f32_e32 v4, v4
	v_add_f32_e32 v3, 1.0, v3
	v_rcp_f32_e32 v3, v3
	v_lshlrev_b32_e32 v10, 16, v112
	v_cndmask_b32_e32 v32, 0, v7, vcc
	v_cndmask_b32_e32 v26, 0, v10, vcc
	v_cvt_pk_bf16_f32 v2, v4, s0
	v_cmp_le_i32_e32 vcc, s60, v34
	ds_write_b16 v194, v2 offset:36832
	v_cvt_pk_bf16_f32 v2, v3, s0
	s_and_b64 vcc, vcc, s[4:5]
	ds_write_b16 v194, v2 offset:36960
	v_cndmask_b32_e32 v2, v170, v34, vcc
	v_mad_i64_i32 v[2:3], s[2:3], v2, s70, v[0:1]
	v_lshl_add_u64 v[4:5], v[2:3], 0, v[196:197]
	v_cmp_gt_i32_e64 s[4:5], s23, v38
	v_lshlrev_b32_e32 v7, 16, v113
	v_lshl_add_u64 v[4:5], v[2:3], 0, v[150:151]
	v_lshl_add_u64 v[2:3], v[2:3], 0, v[152:153]
	v_cndmask_b32_e32 v10, 0, v7, vcc
	v_sub_f32_e32 v3, v39, v21
	v_lshlrev_b32_e32 v4, 16, v114
	v_cndmask_b32_e32 v7, 0, v4, vcc
	v_lshlrev_b32_e32 v2, 16, v115
	v_cndmask_b32_e32 v5, 0, v2, vcc
	v_sub_f32_e32 v2, v19, v21
	v_fma_f32 v2, v141, v2, v21
	v_fmac_f32_e32 v2, v185, v3
	v_sub_f32_e32 v3, v9, v11
	v_fma_f32 v3, v189, v3, v11
	v_sub_f32_e32 v4, v32, v11
	v_mul_f32_e32 v2, 0xbfb8aa3b, v2
	v_fmac_f32_e32 v3, v186, v4
	v_exp_f32_e32 v2, v2
	v_mul_f32_e32 v3, 0xbfb8aa3b, v3
	v_exp_f32_e32 v3, v3
	v_cmp_le_i32_e32 vcc, s60, v38
	v_add_f32_e32 v2, 1.0, v2
	v_rcp_f32_e32 v2, v2
	v_add_f32_e32 v3, 1.0, v3
	v_rcp_f32_e32 v3, v3
	s_and_b64 vcc, vcc, s[4:5]
	v_cvt_pk_bf16_f32 v2, v2, s0
	ds_write_b16 v194, v2 offset:37120
	v_cvt_pk_bf16_f32 v2, v3, s0
	ds_write_b16 v194, v2 offset:37248
	v_cndmask_b32_e32 v2, v170, v38, vcc
	v_sub_f32_e32 v4, v6, v8
	v_mad_i64_i32 v[2:3], s[2:3], v2, s70, v[0:1]
	v_fma_f32 v29, v187, v4, v8
	v_sub_f32_e32 v4, v26, v8
	v_lshl_add_u64 v[40:41], v[2:3], 0, v[196:197]
	v_fmac_f32_e32 v29, v188, v4
	v_lshl_add_u64 v[40:41], v[2:3], 0, v[150:151]
	v_lshl_add_u64 v[2:3], v[2:3], 0, v[152:153]
	v_cmp_gt_i32_e64 s[4:5], s23, v36
	v_sub_f32_e32 v3, v10, v39
	v_lshlrev_b32_e32 v4, 16, v116
	v_cndmask_b32_e32 v19, 0, v4, vcc
	v_sub_f32_e32 v4, v7, v32
	v_lshlrev_b32_e32 v6, 16, v117
	v_cndmask_b32_e32 v9, 0, v6, vcc
	v_lshlrev_b32_e32 v2, 16, v118
	v_cndmask_b32_e32 v6, 0, v2, vcc
	v_sub_f32_e32 v2, v21, v39
	v_fma_f32 v2, v141, v2, v39
	v_fmac_f32_e32 v2, v185, v3
	v_sub_f32_e32 v3, v11, v32
	v_fma_f32 v3, v189, v3, v32
	v_mul_f32_e32 v2, 0xbfb8aa3b, v2
	v_fmac_f32_e32 v3, v186, v4
	v_exp_f32_e32 v2, v2
	v_mul_f32_e32 v3, 0xbfb8aa3b, v3
	v_exp_f32_e32 v3, v3
	v_cmp_le_i32_e32 vcc, s60, v36
	v_add_f32_e32 v2, 1.0, v2
	v_rcp_f32_e32 v2, v2
	v_add_f32_e32 v3, 1.0, v3
	v_rcp_f32_e32 v3, v3
	s_and_b64 vcc, vcc, s[4:5]
	v_cvt_pk_bf16_f32 v2, v2, s0
	ds_write_b16 v194, v2 offset:37408
	v_cvt_pk_bf16_f32 v2, v3, s0
	ds_write_b16 v194, v2 offset:37536
	v_cndmask_b32_e32 v2, v170, v36, vcc
	v_sub_f32_e32 v4, v8, v26
	v_mad_i64_i32 v[2:3], s[2:3], v2, s70, v[0:1]
	v_fma_f32 v35, v187, v4, v26
	v_sub_f32_e32 v4, v5, v26
	v_lshl_add_u64 v[40:41], v[2:3], 0, v[196:197]
	v_fmac_f32_e32 v35, v188, v4
	v_lshl_add_u64 v[40:41], v[2:3], 0, v[150:151]
	v_lshl_add_u64 v[2:3], v[2:3], 0, v[152:153]
	v_lshlrev_b32_e32 v4, 16, v119
	v_sub_f32_e32 v3, v19, v10
	v_cndmask_b32_e32 v43, 0, v4, vcc
	v_sub_f32_e32 v4, v9, v7
	v_lshlrev_b32_e32 v8, 16, v120
	v_or_b32_e32 v40, 13, v170
	v_cndmask_b32_e32 v21, 0, v8, vcc
	v_cmp_gt_i32_e64 s[4:5], s23, v40
	v_lshlrev_b32_e32 v2, 16, v121
	v_cndmask_b32_e32 v11, 0, v2, vcc
	v_sub_f32_e32 v2, v39, v10
	v_fma_f32 v2, v141, v2, v10
	v_fmac_f32_e32 v2, v185, v3
	v_sub_f32_e32 v3, v32, v7
	v_fma_f32 v3, v189, v3, v7
	v_mul_f32_e32 v2, 0xbfb8aa3b, v2
	v_fmac_f32_e32 v3, v186, v4
	v_exp_f32_e32 v2, v2
	v_mul_f32_e32 v3, 0xbfb8aa3b, v3
	v_exp_f32_e32 v3, v3
	v_cmp_le_i32_e32 vcc, s60, v40
	v_add_f32_e32 v2, 1.0, v2
	v_rcp_f32_e32 v2, v2
	v_add_f32_e32 v3, 1.0, v3
	v_rcp_f32_e32 v3, v3
	s_and_b64 vcc, vcc, s[4:5]
	v_cvt_pk_bf16_f32 v2, v2, s0
	ds_write_b16 v194, v2 offset:37696
	v_cvt_pk_bf16_f32 v2, v3, s0
	ds_write_b16 v194, v2 offset:37824
	v_cndmask_b32_e32 v2, v170, v40, vcc
	v_sub_f32_e32 v4, v26, v5
	v_mad_i64_i32 v[2:3], s[2:3], v2, s70, v[0:1]
	v_fma_f32 v39, v187, v4, v5
	v_sub_f32_e32 v4, v6, v5
	v_lshl_add_u64 v[44:45], v[2:3], 0, v[196:197]
	v_fmac_f32_e32 v39, v188, v4
	v_lshl_add_u64 v[44:45], v[2:3], 0, v[150:151]
	v_lshl_add_u64 v[2:3], v[2:3], 0, v[152:153]
	v_sub_f32_e32 v7, v7, v9
	v_fma_f32 v7, v189, v7, v9
	v_sub_f32_e32 v5, v5, v6
	v_fma_f32 v44, v187, v5, v6
	v_sub_f32_e32 v5, v11, v6
	v_or_b32_e32 v26, 14, v170
	v_fmac_f32_e32 v44, v188, v5
	v_cmp_gt_i32_e64 s[4:5], s23, v26
	v_sub_f32_e32 v6, v6, v11
	v_fma_f32 v41, v187, v6, v11
	v_or_b32_e32 v32, 15, v170
	v_lshlrev_b32_e32 v4, 16, v122
	v_cndmask_b32_e32 v4, 0, v4, vcc
	v_lshlrev_b32_e32 v8, 16, v123
	v_cndmask_b32_e32 v3, 0, v8, vcc
	v_sub_f32_e32 v8, v10, v19
	v_fma_f32 v8, v141, v8, v19
	v_sub_f32_e32 v10, v43, v19
	v_fmac_f32_e32 v8, v185, v10
	v_sub_f32_e32 v10, v21, v9
	v_mul_f32_e32 v8, 0xbfb8aa3b, v8
	v_fmac_f32_e32 v7, v186, v10
	v_exp_f32_e32 v8, v8
	v_mul_f32_e32 v7, 0xbfb8aa3b, v7
	v_exp_f32_e32 v7, v7
	v_lshlrev_b32_e32 v2, 16, v124
	v_add_f32_e32 v8, 1.0, v8
	v_rcp_f32_e32 v8, v8
	v_add_f32_e32 v7, 1.0, v7
	v_rcp_f32_e32 v7, v7
	v_cndmask_b32_e32 v2, 0, v2, vcc
	v_cvt_pk_bf16_f32 v5, v8, s0
	v_cmp_le_i32_e32 vcc, s60, v26
	ds_write_b16 v194, v5 offset:37984
	v_cvt_pk_bf16_f32 v5, v7, s0
	s_and_b64 vcc, vcc, s[4:5]
	ds_write_b16 v194, v5 offset:38112
	v_cndmask_b32_e32 v5, v170, v26, vcc
	v_mad_i64_i32 v[46:47], s[2:3], v5, s70, v[0:1]
	v_lshl_add_u64 v[48:49], v[46:47], 0, v[196:197]
	v_lshl_add_u64 v[48:49], v[46:47], 0, v[150:151]
	v_lshl_add_u64 v[46:47], v[46:47], 0, v[152:153]
	v_sub_f32_e32 v9, v9, v21
	v_fma_f32 v9, v189, v9, v21
	v_sub_f32_e32 v6, v2, v11
	v_fmac_f32_e32 v41, v188, v6
	v_cmp_gt_i32_e64 s[4:5], s23, v32
	v_sub_f32_e32 v11, v11, v2
	v_fma_f32 v45, v187, v11, v2
	v_lshlrev_b32_e32 v5, 16, v125
	v_lshlrev_b32_e32 v7, 16, v126
	v_lshlrev_b32_e32 v10, 16, v127
	v_cndmask_b32_e32 v8, 0, v5, vcc
	v_cndmask_b32_e32 v5, 0, v10, vcc
	v_sub_f32_e32 v10, v19, v43
	v_fma_f32 v10, v141, v10, v43
	v_sub_f32_e32 v19, v4, v43
	v_fmac_f32_e32 v10, v185, v19
	v_sub_f32_e32 v19, v3, v21
	v_mul_f32_e32 v10, 0xbfb8aa3b, v10
	v_fmac_f32_e32 v9, v186, v19
	v_exp_f32_e32 v10, v10
	v_mul_f32_e32 v9, 0xbfb8aa3b, v9
	v_exp_f32_e32 v9, v9
	v_cndmask_b32_e32 v7, 0, v7, vcc
	v_add_f32_e32 v10, 1.0, v10
	v_rcp_f32_e32 v10, v10
	v_add_f32_e32 v9, 1.0, v9
	v_rcp_f32_e32 v9, v9
	v_cmp_le_i32_e32 vcc, s60, v32
	v_cvt_pk_bf16_f32 v6, v10, s0
	ds_write_b16 v194, v6 offset:38272
	v_cvt_pk_bf16_f32 v6, v9, s0
	s_and_b64 vcc, vcc, s[4:5]
	ds_write_b16 v194, v6 offset:38400
	v_cndmask_b32_e32 v6, v170, v32, vcc
	v_mad_i64_i32 v[46:47], s[2:3], v6, s70, v[0:1]
	v_lshl_add_u64 v[48:49], v[46:47], 0, v[196:197]
	v_lshl_add_u64 v[48:49], v[46:47], 0, v[150:151]
	v_lshl_add_u64 v[46:47], v[46:47], 0, v[152:153]
	v_sub_f32_e32 v11, v5, v2
	v_fmac_f32_e32 v45, v188, v11
	v_sub_f32_e32 v2, v2, v5
	v_lshlrev_b32_e32 v6, 16, v128
	v_lshlrev_b32_e32 v10, 16, v129
	v_lshlrev_b32_e32 v19, 16, v130
	v_cndmask_b32_e32 v9, 0, v6, vcc
	v_cndmask_b32_e32 v6, 0, v10, vcc
	v_sub_f32_e32 v10, v43, v4
	v_cndmask_b32_e32 v42, 0, v19, vcc
	v_fma_f32 v10, v141, v10, v4
	v_sub_f32_e32 v19, v8, v4
	v_fmac_f32_e32 v10, v185, v19
	v_sub_f32_e32 v19, v21, v3
	v_fma_f32 v19, v189, v19, v3
	v_sub_f32_e32 v21, v7, v3
	v_mul_f32_e32 v10, 0xbfb8aa3b, v10
	v_fmac_f32_e32 v19, v186, v21
	v_exp_f32_e32 v10, v10
	v_mul_f32_e32 v19, 0xbfb8aa3b, v19
	v_exp_f32_e32 v19, v19
	v_sub_f32_e32 v4, v4, v8
	v_add_f32_e32 v10, 1.0, v10
	v_rcp_f32_e32 v10, v10
	v_add_f32_e32 v19, 1.0, v19
	v_rcp_f32_e32 v19, v19
	v_fma_f32 v4, v141, v4, v8
	v_cvt_pk_bf16_f32 v10, v10, s0
	ds_write_b16 v194, v10 offset:38560
	v_cvt_pk_bf16_f32 v10, v19, s0
	ds_write_b16 v194, v10 offset:38688
	v_add_u32_e32 v10, 16, v170
	v_cmp_le_i32_e32 vcc, s60, v10
	v_cmp_gt_i32_e64 s[4:5], s23, v10
	s_and_b64 vcc, vcc, s[4:5]
	v_cndmask_b32_e32 v10, v170, v10, vcc
	v_mad_i64_i32 v[0:1], s[2:3], v10, s70, v[0:1]
	v_lshl_add_u64 v[10:11], v[0:1], 0, v[196:197]
	v_sub_f32_e32 v3, v3, v7
	v_fma_f32 v3, v189, v3, v7
	v_fma_f32 v43, v187, v2, v5
	v_sub_f32_e32 v2, v42, v5
	v_fmac_f32_e32 v43, v188, v2
	v_ashrrev_i32_e32 v21, 31, v20
	v_lshlrev_b32_e32 v19, 16, v131
	v_lshl_add_u64 v[10:11], v[0:1], 0, v[150:151]
	v_lshl_add_u64 v[0:1], v[0:1], 0, v[152:153]
	v_sub_f32_e32 v11, v9, v8
	v_fmac_f32_e32 v4, v185, v11
	v_sub_f32_e32 v11, v6, v7
	v_mul_f32_e32 v4, 0xbfb8aa3b, v4
	v_fmac_f32_e32 v3, v186, v11
	v_exp_f32_e32 v4, v4
	v_mul_f32_e32 v3, 0xbfb8aa3b, v3
	v_exp_f32_e32 v3, v3
	v_cndmask_b32_e32 v1, 0, v19, vcc
	v_add_f32_e32 v4, 1.0, v4
	v_rcp_f32_e32 v4, v4
	v_add_f32_e32 v3, 1.0, v3
	v_rcp_f32_e32 v3, v3
	v_sub_f32_e32 v1, v1, v9
	v_cvt_pk_bf16_f32 v2, v4, s0
	ds_write_b16 v194, v2 offset:38848
	v_cvt_pk_bf16_f32 v2, v3, s0
	ds_write_b16 v194, v2 offset:38976
	v_sub_f32_e32 v2, v8, v9
	v_fmac_f32_e32 v9, v141, v2
	v_sub_f32_e32 v2, v7, v6
	v_fmac_f32_e32 v9, v185, v1
	v_mul_f32_e32 v1, 0xbfb8aa3b, v9
	v_exp_f32_e32 v1, v1
	v_ashrrev_i32_e32 v19, 31, v18
	v_add_f32_e32 v1, 1.0, v1
	v_rcp_f32_e32 v1, v1
	v_lshlrev_b32_e32 v10, 16, v132
	v_cndmask_b32_e32 v10, 0, v10, vcc
	v_sub_f32_e32 v3, v10, v6
	v_fmac_f32_e32 v6, v189, v2
	v_fmac_f32_e32 v6, v186, v3
	v_mul_f32_e32 v2, 0xbfb8aa3b, v6
	v_exp_f32_e32 v2, v2
	v_lshlrev_b32_e32 v0, 16, v133
	v_cndmask_b32_e32 v0, 0, v0, vcc
	v_sub_f32_e32 v3, v5, v42
	v_add_f32_e32 v2, 1.0, v2
	v_rcp_f32_e32 v2, v2
	v_sub_f32_e32 v0, v0, v42
	v_fmac_f32_e32 v42, v187, v3
	v_fmac_f32_e32 v42, v188, v0
	v_cvt_pk_bf16_f32 v0, v1, s0
	ds_write_b16 v194, v0 offset:39136
	v_cvt_pk_bf16_f32 v0, v2, s0
	ds_write_b16 v194, v0 offset:39264
	ds_read_b128 v[46:49], v200 offset:34816
	ds_read_b128 v[8:11], v200 offset:34880
	ds_read_b128 v[4:7], v200 offset:34944
	ds_read_b128 v[0:3], v200 offset:35008
	ds_read_b128 v[50:53], v201 offset:16384
	ds_read_b128 v[54:57], v201 offset:16448
	s_waitcnt lgkmcnt(1)
	v_mfma_f32_16x16x32_bf16 v[50:53], v[46:49], v[50:53], 0
	s_waitcnt lgkmcnt(0)
	v_mfma_f32_16x16x32_bf16 v[50:53], v[8:11], v[54:57], v[50:53]
	ds_read_b128 v[54:57], v201 offset:16512
	s_waitcnt lgkmcnt(0)
	v_mfma_f32_16x16x32_bf16 v[50:53], v[4:7], v[54:57], v[50:53]
	ds_read_b128 v[54:57], v201 offset:16576
	s_waitcnt lgkmcnt(0)
	v_mfma_f32_16x16x32_bf16 v[50:53], v[0:3], v[54:57], v[50:53]
	s_nop 7
	ds_write_b32 v195, v50
	ds_write_b32 v195, v51 offset:256
	ds_write_b32 v195, v52 offset:512
	ds_write_b32 v195, v53 offset:768
	ds_read_b128 v[50:53], v201 offset:20992
	ds_read_b128 v[54:57], v201 offset:21056
	s_waitcnt lgkmcnt(1)
	v_mfma_f32_16x16x32_bf16 v[50:53], v[46:49], v[50:53], 0
	s_waitcnt lgkmcnt(0)
	v_mfma_f32_16x16x32_bf16 v[50:53], v[8:11], v[54:57], v[50:53]
	ds_read_b128 v[54:57], v201 offset:21120
	s_waitcnt lgkmcnt(0)
	v_mfma_f32_16x16x32_bf16 v[50:53], v[4:7], v[54:57], v[50:53]
	ds_read_b128 v[54:57], v201 offset:21184
	s_waitcnt lgkmcnt(0)
	v_mfma_f32_16x16x32_bf16 v[50:53], v[0:3], v[54:57], v[50:53]
	s_nop 7
	ds_write_b32 v195, v50 offset:64
	ds_write_b32 v195, v51 offset:320
	ds_write_b32 v195, v52 offset:576
	ds_write_b32 v195, v53 offset:832
	ds_read_b128 v[50:53], v201 offset:25600
	ds_read_b128 v[54:57], v201 offset:25664
	s_waitcnt lgkmcnt(1)
	v_mfma_f32_16x16x32_bf16 v[50:53], v[46:49], v[50:53], 0
	s_waitcnt lgkmcnt(0)
	v_mfma_f32_16x16x32_bf16 v[50:53], v[8:11], v[54:57], v[50:53]
	ds_read_b128 v[54:57], v201 offset:25728
	s_waitcnt lgkmcnt(0)
	v_mfma_f32_16x16x32_bf16 v[50:53], v[4:7], v[54:57], v[50:53]
	ds_read_b128 v[54:57], v201 offset:25792
	s_waitcnt lgkmcnt(0)
	v_mfma_f32_16x16x32_bf16 v[50:53], v[0:3], v[54:57], v[50:53]
	s_nop 7
	ds_write_b32 v195, v50 offset:128
	ds_write_b32 v195, v51 offset:384
	ds_write_b32 v195, v52 offset:640
	ds_write_b32 v195, v53 offset:896
	ds_read_b128 v[50:53], v201 offset:30208
	s_waitcnt lgkmcnt(0)
	v_mfma_f32_16x16x32_bf16 v[46:49], v[46:49], v[50:53], 0
	ds_read_b128 v[50:53], v201 offset:30272
	s_waitcnt lgkmcnt(0)
	v_mfma_f32_16x16x32_bf16 v[8:11], v[8:11], v[50:53], v[46:49]
	s_nop 4
	ds_read_b128 v[46:49], v201 offset:30336
	s_waitcnt lgkmcnt(0)
	v_mfma_f32_16x16x32_bf16 v[4:7], v[4:7], v[46:49], v[8:11]
	s_nop 2
	ds_read_b128 v[8:11], v201 offset:30400
	s_waitcnt lgkmcnt(0)
	v_mfma_f32_16x16x32_bf16 v[0:3], v[0:3], v[8:11], v[4:7]
	s_nop 7
	ds_write_b32 v195, v0 offset:192
	ds_write_b32 v195, v1 offset:448
	ds_write_b32 v195, v2 offset:704
	ds_write_b32 v195, v3 offset:960
	v_add_f32_dpp v0, v168, v168 quad_perm:[1,0,3,2] row_mask:0xf bank_mask:0xf bound_ctrl:1
	v_add_f32_dpp v6, v169, v169 quad_perm:[1,0,3,2] row_mask:0xf bank_mask:0xf bound_ctrl:1
	ds_read2st64_b32 v[2:3], v202 offset1:1
	v_add_f32_dpp v0, v0, v0 quad_perm:[2,3,0,1] row_mask:0xf bank_mask:0xf bound_ctrl:1
	v_add_f32_dpp v6, v6, v6 quad_perm:[2,3,0,1] row_mask:0xf bank_mask:0xf bound_ctrl:1
	v_lshlrev_b64 v[4:5], 11, v[170:171]
	v_add_f32_dpp v0, v0, v0 row_ror:4 row_mask:0xf bank_mask:0xf bound_ctrl:1
	v_add_f32_dpp v6, v6, v6 row_ror:4 row_mask:0xf bank_mask:0xf bound_ctrl:1
	v_lshl_add_u64 v[4:5], v[144:145], 0, v[4:5]
	v_add_f32_dpp v0, v0, v0 row_ror:8 row_mask:0xf bank_mask:0xf bound_ctrl:1
	v_add_f32_dpp v6, v6, v6 row_ror:8 row_mask:0xf bank_mask:0xf bound_ctrl:1
	v_readlane_b32 s4, v0, 16
	v_readlane_b32 s5, v0, 48
	v_readlane_b32 s2, v0, 0
	v_readlane_b32 s3, v0, 32
	v_mov_b32_e32 v0, s4
	v_mov_b32_e32 v1, s5
	v_pk_add_f32 v[0:1], s[2:3], v[0:1]
	s_nop 0
	v_add_f32_e32 v0, v0, v1
	v_fmamk_f32 v10, v0, 0xbc800000, v168
	v_mul_f32_e32 v0, v10, v10
	v_mov_b32_e32 v1, v197
	s_nop 1
	v_mov_b32_dpp v1, v0 quad_perm:[1,0,3,2] row_mask:0xf bank_mask:0xf
	v_fmac_f32_e32 v1, v10, v10
	s_nop 1
	v_add_f32_dpp v0, v1, v1 quad_perm:[2,3,0,1] row_mask:0xf bank_mask:0xf bound_ctrl:1
	s_nop 1
	v_add_f32_dpp v0, v0, v0 row_ror:4 row_mask:0xf bank_mask:0xf bound_ctrl:1
	s_nop 1
	v_add_f32_dpp v0, v0, v0 row_ror:8 row_mask:0xf bank_mask:0xf bound_ctrl:1
	s_nop 0
	v_readlane_b32 s4, v0, 16
	v_readlane_b32 s5, v0, 48
	v_readlane_b32 s2, v0, 0
	v_readlane_b32 s3, v0, 32
	v_mov_b32_e32 v0, s4
	v_mov_b32_e32 v1, s5
	v_readlane_b32 s4, v6, 16
	v_readlane_b32 s5, v6, 48
	v_pk_add_f32 v[0:1], s[2:3], v[0:1]
	v_readlane_b32 s2, v6, 0
	v_readlane_b32 s3, v6, 32
	v_mov_b32_e32 v6, s4
	v_mov_b32_e32 v7, s5
	v_pk_add_f32 v[6:7], s[2:3], v[6:7]
	v_mov_b32_e32 v9, v0
	v_add_f32_e32 v6, v6, v7
	v_fmac_f32_e32 v169, 0xbc800000, v6
	v_mul_f32_e32 v6, v169, v169
	v_mov_b32_e32 v7, v197
	s_nop 1
	v_mov_b32_dpp v7, v6 quad_perm:[1,0,3,2] row_mask:0xf bank_mask:0xf
	v_fmac_f32_e32 v7, v169, v169
	s_nop 1
	v_add_f32_dpp v6, v7, v7 quad_perm:[2,3,0,1] row_mask:0xf bank_mask:0xf bound_ctrl:1
	s_nop 1
	v_add_f32_dpp v6, v6, v6 row_ror:4 row_mask:0xf bank_mask:0xf bound_ctrl:1
	s_nop 1
	v_add_f32_dpp v6, v6, v6 row_ror:8 row_mask:0xf bank_mask:0xf bound_ctrl:1
	s_nop 0
	v_readlane_b32 s4, v6, 16
	v_readlane_b32 s5, v6, 48
	v_readlane_b32 s2, v6, 0
	v_readlane_b32 s3, v6, 32
	v_mov_b32_e32 v6, s4
	v_mov_b32_e32 v7, s5
	v_pk_add_f32 v[6:7], s[2:3], v[6:7]
	s_mov_b32 s2, 0x3a27c5ac
	v_mov_b32_e32 v8, v6
	v_mov_b32_e32 v0, v7
	v_pk_add_f32 v[6:7], v[8:9], v[0:1]
	v_mov_b64_e32 v[0:1], s[2:3]
	v_pk_fma_f32 v[6:7], v[6:7], s[52:53], v[0:1] op_sel_hi:[1,0,0]
	s_nop 0
	v_mul_f32_e32 v8, 0x4b800000, v7
	v_cmp_gt_f32_e64 s[4:5], s69, v7
	v_cmp_gt_f32_e32 vcc, s69, v6
	s_nop 0
	v_cndmask_b32_e64 v7, v7, v8, s[4:5]
	v_rsq_f32_e32 v7, v7
	s_nop 0
	v_mul_f32_e32 v8, 0x45800000, v7
	v_cndmask_b32_e64 v7, v7, v8, s[4:5]
	v_mul_f32_e32 v7, v10, v7
	v_fma_f32 v7, v181, v7, v184
	v_fmac_f32_e32 v7, s42, v13
	s_waitcnt lgkmcnt(0)
	v_mul_f32_e32 v2, v2, v7
	v_cvt_pk_bf16_f32 v2, v2, s0
	global_store_short v[4:5], v2, off
	v_mul_f32_e32 v2, 0x4b800000, v6
	v_cndmask_b32_e32 v2, v6, v2, vcc
	v_rsq_f32_e32 v2, v2
	v_add_f32_dpp v8, v167, v167 quad_perm:[1,0,3,2] row_mask:0xf bank_mask:0xf bound_ctrl:1
	v_readlane_b32 s42, v33, 2
	v_lshlrev_b64 v[6:7], 11, v[18:19]
	v_mul_f32_e32 v4, 0x45800000, v2
	v_cndmask_b32_e32 v2, v2, v4, vcc
	v_mul_f32_e32 v2, v169, v2
	v_fma_f32 v2, v181, v2, v184
	v_fmac_f32_e32 v2, s43, v17
	v_mul_f32_e32 v2, v3, v2
	v_cvt_pk_bf16_f32 v4, v2, s0
	v_lshlrev_b64 v[2:3], 11, v[20:21]
	v_lshl_add_u64 v[2:3], v[144:145], 0, v[2:3]
	global_store_short v[2:3], v4, off
	v_add_f32_dpp v4, v166, v166 quad_perm:[1,0,3,2] row_mask:0xf bank_mask:0xf bound_ctrl:1
	v_add_f32_dpp v8, v8, v8 quad_perm:[2,3,0,1] row_mask:0xf bank_mask:0xf bound_ctrl:1
	ds_read2st64_b32 v[2:3], v202 offset0:2 offset1:3
	v_add_f32_dpp v4, v4, v4 quad_perm:[2,3,0,1] row_mask:0xf bank_mask:0xf bound_ctrl:1
	v_add_f32_dpp v8, v8, v8 row_ror:4 row_mask:0xf bank_mask:0xf bound_ctrl:1
	v_lshl_add_u64 v[6:7], v[144:145], 0, v[6:7]
	v_add_f32_dpp v4, v4, v4 row_ror:4 row_mask:0xf bank_mask:0xf bound_ctrl:1
	v_add_f32_dpp v8, v8, v8 row_ror:8 row_mask:0xf bank_mask:0xf bound_ctrl:1
	v_readlane_b32 s43, v33, 3
	v_add_f32_dpp v4, v4, v4 row_ror:8 row_mask:0xf bank_mask:0xf bound_ctrl:1
	v_ashrrev_i32_e32 v17, 31, v16
	v_readlane_b32 s4, v4, 16
	v_readlane_b32 s5, v4, 48
	v_readlane_b32 s2, v4, 0
	v_readlane_b32 s3, v4, 32
	v_mov_b32_e32 v4, s4
	v_mov_b32_e32 v5, s5
	v_pk_add_f32 v[4:5], s[2:3], v[4:5]
	s_nop 0
	v_add_f32_e32 v4, v4, v5
	v_fmamk_f32 v13, v4, 0xbc800000, v166
	v_mul_f32_e32 v4, v13, v13
	v_mov_b32_e32 v5, v197
	s_nop 1
	v_mov_b32_dpp v5, v4 quad_perm:[1,0,3,2] row_mask:0xf bank_mask:0xf
	v_fmac_f32_e32 v5, v13, v13
	s_nop 1
	v_add_f32_dpp v4, v5, v5 quad_perm:[2,3,0,1] row_mask:0xf bank_mask:0xf bound_ctrl:1
	s_nop 1
	v_add_f32_dpp v4, v4, v4 row_ror:4 row_mask:0xf bank_mask:0xf bound_ctrl:1
	s_nop 1
	v_add_f32_dpp v4, v4, v4 row_ror:8 row_mask:0xf bank_mask:0xf bound_ctrl:1
	s_nop 0
	v_readlane_b32 s4, v4, 16
	v_readlane_b32 s5, v4, 48
	v_readlane_b32 s2, v4, 0
	v_readlane_b32 s3, v4, 32
	v_mov_b32_e32 v4, s4
	v_mov_b32_e32 v5, s5
	v_readlane_b32 s4, v8, 16
	v_readlane_b32 s5, v8, 48
	v_pk_add_f32 v[4:5], s[2:3], v[4:5]
	v_readlane_b32 s2, v8, 0
	v_readlane_b32 s3, v8, 32
	v_mov_b32_e32 v8, s4
	v_mov_b32_e32 v9, s5
	v_pk_add_f32 v[8:9], s[2:3], v[8:9]
	v_mov_b32_e32 v11, v4
	v_add_f32_e32 v8, v8, v9
	v_fmac_f32_e32 v167, 0xbc800000, v8
	v_mul_f32_e32 v8, v167, v167
	v_mov_b32_e32 v9, v197
	s_nop 1
	v_mov_b32_dpp v9, v8 quad_perm:[1,0,3,2] row_mask:0xf bank_mask:0xf
	v_fmac_f32_e32 v9, v167, v167
	s_nop 1
	v_add_f32_dpp v8, v9, v9 quad_perm:[2,3,0,1] row_mask:0xf bank_mask:0xf bound_ctrl:1
	s_nop 1
	v_add_f32_dpp v8, v8, v8 row_ror:4 row_mask:0xf bank_mask:0xf bound_ctrl:1
	s_nop 1
	v_add_f32_dpp v8, v8, v8 row_ror:8 row_mask:0xf bank_mask:0xf bound_ctrl:1
	s_nop 0
	v_readlane_b32 s4, v8, 16
	v_readlane_b32 s5, v8, 48
	v_readlane_b32 s2, v8, 0
	v_readlane_b32 s3, v8, 32
	v_mov_b32_e32 v8, s4
	v_mov_b32_e32 v9, s5
	v_pk_add_f32 v[8:9], s[2:3], v[8:9]
	v_readlane_b32 s2, v33, 4
	v_mov_b32_e32 v10, v8
	v_mov_b32_e32 v4, v9
	v_pk_add_f32 v[4:5], v[10:11], v[4:5]
	s_nop 0
	v_pk_fma_f32 v[4:5], v[4:5], s[52:53], v[0:1] op_sel_hi:[1,0,0]
	s_nop 0
	v_mul_f32_e32 v8, 0x4b800000, v5
	v_cmp_gt_f32_e64 s[4:5], s69, v5
	v_cmp_gt_f32_e32 vcc, s69, v4
	s_nop 0
	v_cndmask_b32_e64 v5, v5, v8, s[4:5]
	v_rsq_f32_e32 v5, v5
	s_nop 0
	v_mul_f32_e32 v8, 0x45800000, v5
	v_cndmask_b32_e64 v5, v5, v8, s[4:5]
	v_mul_f32_e32 v5, v13, v5
	v_fma_f32 v5, v181, v5, v184
	v_fmac_f32_e32 v5, s42, v23
	s_waitcnt lgkmcnt(0)
	v_mul_f32_e32 v2, v2, v5
	v_cvt_pk_bf16_f32 v2, v2, s0
	global_store_short v[6:7], v2, off
	v_mul_f32_e32 v2, 0x4b800000, v4
	v_cndmask_b32_e32 v2, v4, v2, vcc
	v_rsq_f32_e32 v2, v2
	v_add_f32_dpp v8, v165, v165 quad_perm:[1,0,3,2] row_mask:0xf bank_mask:0xf bound_ctrl:1
	v_lshlrev_b64 v[6:7], 11, v[16:17]
	v_lshl_add_u64 v[6:7], v[144:145], 0, v[6:7]
	v_mul_f32_e32 v4, 0x45800000, v2
	v_cndmask_b32_e32 v2, v2, v4, vcc
	v_mul_f32_e32 v2, v167, v2
	v_fma_f32 v2, v181, v2, v184
	v_fmac_f32_e32 v2, s43, v25
	v_mul_f32_e32 v2, v3, v2
	v_ashrrev_i32_e32 v25, 31, v24
	v_cvt_pk_bf16_f32 v4, v2, s0
	v_lshlrev_b64 v[2:3], 11, v[24:25]
	v_lshl_add_u64 v[2:3], v[144:145], 0, v[2:3]
	global_store_short v[2:3], v4, off
	v_add_f32_dpp v4, v164, v164 quad_perm:[1,0,3,2] row_mask:0xf bank_mask:0xf bound_ctrl:1
	v_add_f32_dpp v8, v8, v8 quad_perm:[2,3,0,1] row_mask:0xf bank_mask:0xf bound_ctrl:1
	ds_read2st64_b32 v[2:3], v202 offset0:4 offset1:5
	v_add_f32_dpp v4, v4, v4 quad_perm:[2,3,0,1] row_mask:0xf bank_mask:0xf bound_ctrl:1
	v_add_f32_dpp v8, v8, v8 row_ror:4 row_mask:0xf bank_mask:0xf bound_ctrl:1
	v_ashrrev_i32_e32 v23, 31, v22
	v_add_f32_dpp v4, v4, v4 row_ror:4 row_mask:0xf bank_mask:0xf bound_ctrl:1
	v_add_f32_dpp v8, v8, v8 row_ror:8 row_mask:0xf bank_mask:0xf bound_ctrl:1
	s_nop 0
	v_add_f32_dpp v4, v4, v4 row_ror:8 row_mask:0xf bank_mask:0xf bound_ctrl:1
	v_readlane_b32 s43, v8, 48
	v_readlane_b32 s3, v4, 16
	v_readlane_b32 s42, v4, 48
	v_readlane_b32 s4, v4, 0
	v_readlane_b32 s5, v4, 32
	v_mov_b32_e32 v4, s3
	v_mov_b32_e32 v5, s42
	v_pk_add_f32 v[4:5], s[4:5], v[4:5]
	v_mov_b32_e32 v9, s43
	v_add_f32_e32 v4, v4, v5
	v_fmamk_f32 v13, v4, 0xbc800000, v164
	v_mul_f32_e32 v4, v13, v13
	v_mov_b32_e32 v5, v197
	s_nop 1
	v_mov_b32_dpp v5, v4 quad_perm:[1,0,3,2] row_mask:0xf bank_mask:0xf
	v_fmac_f32_e32 v5, v13, v13
	s_nop 1
	v_add_f32_dpp v4, v5, v5 quad_perm:[2,3,0,1] row_mask:0xf bank_mask:0xf bound_ctrl:1
	s_nop 1
	v_add_f32_dpp v4, v4, v4 row_ror:4 row_mask:0xf bank_mask:0xf bound_ctrl:1
	s_nop 1
	v_add_f32_dpp v4, v4, v4 row_ror:8 row_mask:0xf bank_mask:0xf bound_ctrl:1
	s_nop 0
	v_readlane_b32 s3, v4, 16
	v_readlane_b32 s42, v4, 48
	v_readlane_b32 s4, v4, 0
	v_readlane_b32 s5, v4, 32
	v_mov_b32_e32 v4, s3
	v_mov_b32_e32 v5, s42
	v_readlane_b32 s42, v8, 16
	v_pk_add_f32 v[4:5], s[4:5], v[4:5]
	v_readlane_b32 s4, v8, 0
	v_readlane_b32 s5, v8, 32
	v_mov_b32_e32 v8, s42
	v_mov_b32_e32 v11, v4
	v_pk_add_f32 v[8:9], s[4:5], v[8:9]
	v_readlane_b32 s3, v33, 5
	v_add_f32_e32 v8, v8, v9
	v_fmac_f32_e32 v165, 0xbc800000, v8
	v_mul_f32_e32 v8, v165, v165
	v_mov_b32_e32 v9, v197
	s_nop 1
	v_mov_b32_dpp v9, v8 quad_perm:[1,0,3,2] row_mask:0xf bank_mask:0xf
	v_fmac_f32_e32 v9, v165, v165
	s_nop 1
	v_add_f32_dpp v8, v9, v9 quad_perm:[2,3,0,1] row_mask:0xf bank_mask:0xf bound_ctrl:1
	s_nop 1
	v_add_f32_dpp v8, v8, v8 row_ror:4 row_mask:0xf bank_mask:0xf bound_ctrl:1
	s_nop 1
	v_add_f32_dpp v8, v8, v8 row_ror:8 row_mask:0xf bank_mask:0xf bound_ctrl:1
	s_nop 0
	v_readlane_b32 s42, v8, 16
	v_readlane_b32 s43, v8, 48
	v_readlane_b32 s4, v8, 0
	v_readlane_b32 s5, v8, 32
	v_mov_b32_e32 v8, s42
	v_mov_b32_e32 v9, s43
	v_pk_add_f32 v[8:9], s[4:5], v[8:9]
	s_nop 0
	v_mov_b32_e32 v10, v8
	v_mov_b32_e32 v4, v9
	v_pk_add_f32 v[4:5], v[10:11], v[4:5]
	s_nop 0
	v_pk_fma_f32 v[4:5], v[4:5], s[52:53], v[0:1] op_sel_hi:[1,0,0]
	s_nop 0
	v_mul_f32_e32 v8, 0x4b800000, v5
	v_cmp_gt_f32_e64 s[4:5], s69, v5
	v_cmp_gt_f32_e32 vcc, s69, v4
	s_nop 0
	v_cndmask_b32_e64 v5, v5, v8, s[4:5]
	v_rsq_f32_e32 v5, v5
	s_nop 0
	v_mul_f32_e32 v8, 0x45800000, v5
	v_cndmask_b32_e64 v5, v5, v8, s[4:5]
	v_mul_f32_e32 v5, v13, v5
	v_fma_f32 v5, v181, v5, v184
	v_fmac_f32_e32 v5, s2, v31
	s_waitcnt lgkmcnt(0)
	v_mul_f32_e32 v2, v2, v5
	v_cvt_pk_bf16_f32 v2, v2, s0
	global_store_short v[6:7], v2, off
	v_mul_f32_e32 v2, 0x4b800000, v4
	v_cndmask_b32_e32 v2, v4, v2, vcc
	v_rsq_f32_e32 v2, v2
	v_ashrrev_i32_e32 v31, 31, v30
	v_add_f32_dpp v8, v163, v163 quad_perm:[1,0,3,2] row_mask:0xf bank_mask:0xf bound_ctrl:1
	v_readlane_b32 s2, v33, 6
	v_mul_f32_e32 v4, 0x45800000, v2
	v_cndmask_b32_e32 v2, v2, v4, vcc
	v_mul_f32_e32 v2, v165, v2
	v_fma_f32 v2, v181, v2, v184
	v_fmac_f32_e32 v2, s3, v37
	v_mul_f32_e32 v2, v3, v2
	v_cvt_pk_bf16_f32 v4, v2, s0
	v_lshlrev_b64 v[2:3], 11, v[30:31]
	v_lshl_add_u64 v[2:3], v[144:145], 0, v[2:3]
	global_store_short v[2:3], v4, off
	v_add_f32_dpp v4, v162, v162 quad_perm:[1,0,3,2] row_mask:0xf bank_mask:0xf bound_ctrl:1
	v_add_f32_dpp v8, v8, v8 quad_perm:[2,3,0,1] row_mask:0xf bank_mask:0xf bound_ctrl:1
	ds_read2st64_b32 v[2:3], v202 offset0:6 offset1:7
	v_add_f32_dpp v4, v4, v4 quad_perm:[2,3,0,1] row_mask:0xf bank_mask:0xf bound_ctrl:1
	v_add_f32_dpp v8, v8, v8 row_ror:4 row_mask:0xf bank_mask:0xf bound_ctrl:1
	v_ashrrev_i32_e32 v13, 31, v12
	v_add_f32_dpp v4, v4, v4 row_ror:4 row_mask:0xf bank_mask:0xf bound_ctrl:1
	v_add_f32_dpp v8, v8, v8 row_ror:8 row_mask:0xf bank_mask:0xf bound_ctrl:1
	v_lshlrev_b64 v[6:7], 11, v[12:13]
	v_add_f32_dpp v4, v4, v4 row_ror:8 row_mask:0xf bank_mask:0xf bound_ctrl:1
	v_readlane_b32 s43, v8, 48
	v_readlane_b32 s3, v4, 16
	v_readlane_b32 s42, v4, 48
	v_readlane_b32 s4, v4, 0
	v_readlane_b32 s5, v4, 32
	v_mov_b32_e32 v4, s3
	v_mov_b32_e32 v5, s42
	v_pk_add_f32 v[4:5], s[4:5], v[4:5]
	v_mov_b32_e32 v9, s43
	v_add_f32_e32 v4, v4, v5
	v_fmamk_f32 v16, v4, 0xbc800000, v162
	v_mul_f32_e32 v4, v16, v16
	v_mov_b32_e32 v5, v197
	v_lshl_add_u64 v[6:7], v[144:145], 0, v[6:7]
	v_ashrrev_i32_e32 v37, 31, v36
	v_mov_b32_dpp v5, v4 quad_perm:[1,0,3,2] row_mask:0xf bank_mask:0xf
	v_fmac_f32_e32 v5, v16, v16
	s_nop 1
	v_add_f32_dpp v4, v5, v5 quad_perm:[2,3,0,1] row_mask:0xf bank_mask:0xf bound_ctrl:1
	s_nop 1
	v_add_f32_dpp v4, v4, v4 row_ror:4 row_mask:0xf bank_mask:0xf bound_ctrl:1
	s_nop 1
	v_add_f32_dpp v4, v4, v4 row_ror:8 row_mask:0xf bank_mask:0xf bound_ctrl:1
	s_nop 0
	v_readlane_b32 s3, v4, 16
	v_readlane_b32 s42, v4, 48
	v_readlane_b32 s4, v4, 0
	v_readlane_b32 s5, v4, 32
	v_mov_b32_e32 v4, s3
	v_mov_b32_e32 v5, s42
	v_readlane_b32 s42, v8, 16
	v_pk_add_f32 v[4:5], s[4:5], v[4:5]
	v_readlane_b32 s4, v8, 0
	v_readlane_b32 s5, v8, 32
	v_mov_b32_e32 v8, s42
	v_mov_b32_e32 v11, v4
	v_pk_add_f32 v[8:9], s[4:5], v[8:9]
	v_readlane_b32 s3, v33, 7
	v_add_f32_e32 v8, v8, v9
	v_fmac_f32_e32 v163, 0xbc800000, v8
	v_mul_f32_e32 v8, v163, v163
	v_mov_b32_e32 v9, v197
	s_nop 1
	v_mov_b32_dpp v9, v8 quad_perm:[1,0,3,2] row_mask:0xf bank_mask:0xf
	v_fmac_f32_e32 v9, v163, v163
	s_nop 1
	v_add_f32_dpp v8, v9, v9 quad_perm:[2,3,0,1] row_mask:0xf bank_mask:0xf bound_ctrl:1
	s_nop 1
	v_add_f32_dpp v8, v8, v8 row_ror:4 row_mask:0xf bank_mask:0xf bound_ctrl:1
	s_nop 1
	v_add_f32_dpp v8, v8, v8 row_ror:8 row_mask:0xf bank_mask:0xf bound_ctrl:1
	s_nop 0
	v_readlane_b32 s42, v8, 16
	v_readlane_b32 s43, v8, 48
	v_readlane_b32 s4, v8, 0
	v_readlane_b32 s5, v8, 32
	v_mov_b32_e32 v8, s42
	v_mov_b32_e32 v9, s43
	v_pk_add_f32 v[8:9], s[4:5], v[8:9]
	v_readlane_b32 s42, v33, 8
	v_mov_b32_e32 v10, v8
	v_mov_b32_e32 v4, v9
	v_pk_add_f32 v[4:5], v[10:11], v[4:5]
	v_readlane_b32 s43, v33, 9
	v_pk_fma_f32 v[4:5], v[4:5], s[52:53], v[0:1] op_sel_hi:[1,0,0]
	s_nop 0
	v_mul_f32_e32 v8, 0x4b800000, v5
	v_cmp_gt_f32_e64 s[4:5], s69, v5
	v_cmp_gt_f32_e32 vcc, s69, v4
	s_nop 0
	v_cndmask_b32_e64 v5, v5, v8, s[4:5]
	v_rsq_f32_e32 v5, v5
	s_nop 0
	v_mul_f32_e32 v8, 0x45800000, v5
	v_cndmask_b32_e64 v5, v5, v8, s[4:5]
	v_mul_f32_e32 v5, v16, v5
	v_fma_f32 v5, v181, v5, v184
	v_fmac_f32_e32 v5, s2, v15
	s_waitcnt lgkmcnt(0)
	v_mul_f32_e32 v2, v2, v5
	v_cvt_pk_bf16_f32 v2, v2, s0
	global_store_short v[6:7], v2, off
	v_mul_f32_e32 v2, 0x4b800000, v4
	v_cndmask_b32_e32 v2, v4, v2, vcc
	v_rsq_f32_e32 v2, v2
	v_ashrrev_i32_e32 v15, 31, v14
	v_add_f32_dpp v8, v161, v161 quad_perm:[1,0,3,2] row_mask:0xf bank_mask:0xf bound_ctrl:1
	v_lshlrev_b64 v[6:7], 11, v[22:23]
	v_mul_f32_e32 v4, 0x45800000, v2
	v_cndmask_b32_e32 v2, v2, v4, vcc
	v_mul_f32_e32 v2, v163, v2
	v_fma_f32 v2, v181, v2, v184
	v_fmac_f32_e32 v2, s3, v27
	v_mul_f32_e32 v2, v3, v2
	v_cvt_pk_bf16_f32 v4, v2, s0
	v_lshlrev_b64 v[2:3], 11, v[14:15]
	v_lshl_add_u64 v[2:3], v[144:145], 0, v[2:3]
	global_store_short v[2:3], v4, off
	v_add_f32_dpp v4, v160, v160 quad_perm:[1,0,3,2] row_mask:0xf bank_mask:0xf bound_ctrl:1
	v_add_f32_dpp v8, v8, v8 quad_perm:[2,3,0,1] row_mask:0xf bank_mask:0xf bound_ctrl:1
	ds_read2st64_b32 v[2:3], v202 offset0:8 offset1:9
	v_add_f32_dpp v4, v4, v4 quad_perm:[2,3,0,1] row_mask:0xf bank_mask:0xf bound_ctrl:1
	v_add_f32_dpp v8, v8, v8 row_ror:4 row_mask:0xf bank_mask:0xf bound_ctrl:1
	v_lshl_add_u64 v[6:7], v[144:145], 0, v[6:7]
	v_add_f32_dpp v4, v4, v4 row_ror:4 row_mask:0xf bank_mask:0xf bound_ctrl:1
	v_add_f32_dpp v8, v8, v8 row_ror:8 row_mask:0xf bank_mask:0xf bound_ctrl:1
	v_ashrrev_i32_e32 v27, 31, v26
	v_add_f32_dpp v4, v4, v4 row_ror:8 row_mask:0xf bank_mask:0xf bound_ctrl:1
	s_nop 0
	v_readlane_b32 s4, v4, 16
	v_readlane_b32 s5, v4, 48
	v_readlane_b32 s2, v4, 0
	v_readlane_b32 s3, v4, 32
	v_mov_b32_e32 v4, s4
	v_mov_b32_e32 v5, s5
	v_pk_add_f32 v[4:5], s[2:3], v[4:5]
	s_nop 0
	v_add_f32_e32 v4, v4, v5
	v_fmamk_f32 v12, v4, 0xbc800000, v160
	v_mul_f32_e32 v4, v12, v12
	v_mov_b32_e32 v5, v197
	s_nop 1
	v_mov_b32_dpp v5, v4 quad_perm:[1,0,3,2] row_mask:0xf bank_mask:0xf
	v_fmac_f32_e32 v5, v12, v12
	s_nop 1
	v_add_f32_dpp v4, v5, v5 quad_perm:[2,3,0,1] row_mask:0xf bank_mask:0xf bound_ctrl:1
	s_nop 1
	v_add_f32_dpp v4, v4, v4 row_ror:4 row_mask:0xf bank_mask:0xf bound_ctrl:1
	s_nop 1
	v_add_f32_dpp v4, v4, v4 row_ror:8 row_mask:0xf bank_mask:0xf bound_ctrl:1
	s_nop 0
	v_readlane_b32 s4, v4, 16
	v_readlane_b32 s5, v4, 48
	v_readlane_b32 s2, v4, 0
	v_readlane_b32 s3, v4, 32
	v_mov_b32_e32 v4, s4
	v_mov_b32_e32 v5, s5
	v_readlane_b32 s4, v8, 16
	v_readlane_b32 s5, v8, 48
	v_pk_add_f32 v[4:5], s[2:3], v[4:5]
	v_readlane_b32 s2, v8, 0
	v_readlane_b32 s3, v8, 32
	v_mov_b32_e32 v8, s4
	v_mov_b32_e32 v9, s5
	v_pk_add_f32 v[8:9], s[2:3], v[8:9]
	v_mov_b32_e32 v11, v4
	v_add_f32_e32 v8, v8, v9
	v_fmac_f32_e32 v161, 0xbc800000, v8
	v_mul_f32_e32 v8, v161, v161
	v_mov_b32_e32 v9, v197
	s_nop 1
	v_mov_b32_dpp v9, v8 quad_perm:[1,0,3,2] row_mask:0xf bank_mask:0xf
	v_fmac_f32_e32 v9, v161, v161
	s_nop 1
	v_add_f32_dpp v8, v9, v9 quad_perm:[2,3,0,1] row_mask:0xf bank_mask:0xf bound_ctrl:1
	s_nop 1
	v_add_f32_dpp v8, v8, v8 row_ror:4 row_mask:0xf bank_mask:0xf bound_ctrl:1
	s_nop 1
	v_add_f32_dpp v8, v8, v8 row_ror:8 row_mask:0xf bank_mask:0xf bound_ctrl:1
	s_nop 0
	v_readlane_b32 s4, v8, 16
	v_readlane_b32 s5, v8, 48
	v_readlane_b32 s2, v8, 0
	v_readlane_b32 s3, v8, 32
	v_mov_b32_e32 v8, s4
	v_mov_b32_e32 v9, s5
	v_pk_add_f32 v[8:9], s[2:3], v[8:9]
	s_nop 0
	v_mov_b32_e32 v10, v8
	v_mov_b32_e32 v4, v9
	v_pk_add_f32 v[4:5], v[10:11], v[4:5]
	s_nop 0
	v_pk_fma_f32 v[4:5], v[4:5], s[52:53], v[0:1] op_sel_hi:[1,0,0]
	s_nop 0
	v_mul_f32_e32 v8, 0x4b800000, v5
	v_cmp_gt_f32_e64 s[4:5], s69, v5
	v_cmp_gt_f32_e32 vcc, s69, v4
	s_nop 0
	v_cndmask_b32_e64 v5, v5, v8, s[4:5]
	v_rsq_f32_e32 v5, v5
	s_nop 0
	v_mul_f32_e32 v8, 0x45800000, v5
	v_cndmask_b32_e64 v5, v5, v8, s[4:5]
	v_mul_f32_e32 v5, v12, v5
	v_fma_f32 v5, v181, v5, v184
	v_fmac_f32_e32 v5, s42, v29
	s_waitcnt lgkmcnt(0)
	v_mul_f32_e32 v2, v2, v5
	v_cvt_pk_bf16_f32 v2, v2, s0
	global_store_short v[6:7], v2, off
	v_mul_f32_e32 v2, 0x4b800000, v4
	v_cndmask_b32_e32 v2, v4, v2, vcc
	v_rsq_f32_e32 v2, v2
	v_ashrrev_i32_e32 v29, 31, v28
	v_add_f32_dpp v8, v159, v159 quad_perm:[1,0,3,2] row_mask:0xf bank_mask:0xf bound_ctrl:1
	v_readlane_b32 s42, v33, 10
	v_mul_f32_e32 v4, 0x45800000, v2
	v_cndmask_b32_e32 v2, v2, v4, vcc
	v_mul_f32_e32 v2, v161, v2
	v_fma_f32 v2, v181, v2, v184
	v_fmac_f32_e32 v2, s43, v35
	v_mul_f32_e32 v2, v3, v2
	v_cvt_pk_bf16_f32 v4, v2, s0
	v_lshlrev_b64 v[2:3], 11, v[28:29]
	v_lshl_add_u64 v[2:3], v[144:145], 0, v[2:3]
	global_store_short v[2:3], v4, off
	v_add_f32_dpp v4, v158, v158 quad_perm:[1,0,3,2] row_mask:0xf bank_mask:0xf bound_ctrl:1
	v_add_f32_dpp v8, v8, v8 quad_perm:[2,3,0,1] row_mask:0xf bank_mask:0xf bound_ctrl:1
	ds_read2st64_b32 v[2:3], v202 offset0:10 offset1:11
	v_add_f32_dpp v4, v4, v4 quad_perm:[2,3,0,1] row_mask:0xf bank_mask:0xf bound_ctrl:1
	v_add_f32_dpp v8, v8, v8 row_ror:4 row_mask:0xf bank_mask:0xf bound_ctrl:1
	v_ashrrev_i32_e32 v35, 31, v34
	v_add_f32_dpp v4, v4, v4 row_ror:4 row_mask:0xf bank_mask:0xf bound_ctrl:1
	v_add_f32_dpp v8, v8, v8 row_ror:8 row_mask:0xf bank_mask:0xf bound_ctrl:1
	v_lshlrev_b64 v[6:7], 11, v[34:35]
	v_add_f32_dpp v4, v4, v4 row_ror:8 row_mask:0xf bank_mask:0xf bound_ctrl:1
	v_lshl_add_u64 v[6:7], v[144:145], 0, v[6:7]
	v_readlane_b32 s4, v4, 16
	v_readlane_b32 s5, v4, 48
	v_readlane_b32 s2, v4, 0
	v_readlane_b32 s3, v4, 32
	v_mov_b32_e32 v4, s4
	v_mov_b32_e32 v5, s5
	v_pk_add_f32 v[4:5], s[2:3], v[4:5]
	v_readlane_b32 s43, v33, 11
	v_add_f32_e32 v4, v4, v5
	v_fmamk_f32 v12, v4, 0xbc800000, v158
	v_mul_f32_e32 v4, v12, v12
	v_mov_b32_e32 v5, v197
	s_nop 1
	v_mov_b32_dpp v5, v4 quad_perm:[1,0,3,2] row_mask:0xf bank_mask:0xf
	v_fmac_f32_e32 v5, v12, v12
	s_nop 1
	v_add_f32_dpp v4, v5, v5 quad_perm:[2,3,0,1] row_mask:0xf bank_mask:0xf bound_ctrl:1
	s_nop 1
	v_add_f32_dpp v4, v4, v4 row_ror:4 row_mask:0xf bank_mask:0xf bound_ctrl:1
	s_nop 1
	v_add_f32_dpp v4, v4, v4 row_ror:8 row_mask:0xf bank_mask:0xf bound_ctrl:1
	s_nop 0
	v_readlane_b32 s4, v4, 16
	v_readlane_b32 s5, v4, 48
	v_readlane_b32 s2, v4, 0
	v_readlane_b32 s3, v4, 32
	v_mov_b32_e32 v4, s4
	v_mov_b32_e32 v5, s5
	v_readlane_b32 s4, v8, 16
	v_readlane_b32 s5, v8, 48
	v_pk_add_f32 v[4:5], s[2:3], v[4:5]
	v_readlane_b32 s2, v8, 0
	v_readlane_b32 s3, v8, 32
	v_mov_b32_e32 v8, s4
	v_mov_b32_e32 v9, s5
	v_pk_add_f32 v[8:9], s[2:3], v[8:9]
	v_mov_b32_e32 v11, v4
	v_add_f32_e32 v8, v8, v9
	v_fmac_f32_e32 v159, 0xbc800000, v8
	v_mul_f32_e32 v8, v159, v159
	v_mov_b32_e32 v9, v197
	s_nop 1
	v_mov_b32_dpp v9, v8 quad_perm:[1,0,3,2] row_mask:0xf bank_mask:0xf
	v_fmac_f32_e32 v9, v159, v159
	s_nop 1
	v_add_f32_dpp v8, v9, v9 quad_perm:[2,3,0,1] row_mask:0xf bank_mask:0xf bound_ctrl:1
	s_nop 1
	v_add_f32_dpp v8, v8, v8 row_ror:4 row_mask:0xf bank_mask:0xf bound_ctrl:1
	s_nop 1
	v_add_f32_dpp v8, v8, v8 row_ror:8 row_mask:0xf bank_mask:0xf bound_ctrl:1
	s_nop 0
	v_readlane_b32 s4, v8, 16
	v_readlane_b32 s5, v8, 48
	v_readlane_b32 s2, v8, 0
	v_readlane_b32 s3, v8, 32
	v_mov_b32_e32 v8, s4
	v_mov_b32_e32 v9, s5
	v_pk_add_f32 v[8:9], s[2:3], v[8:9]
	v_readlane_b32 s2, v33, 12
	v_mov_b32_e32 v10, v8
	v_mov_b32_e32 v4, v9
	v_pk_add_f32 v[4:5], v[10:11], v[4:5]
	s_nop 0
	v_pk_fma_f32 v[4:5], v[4:5], s[52:53], v[0:1] op_sel_hi:[1,0,0]
	s_nop 0
	v_mul_f32_e32 v8, 0x4b800000, v5
	v_cmp_gt_f32_e64 s[4:5], s69, v5
	v_cmp_gt_f32_e32 vcc, s69, v4
	s_nop 0
	v_cndmask_b32_e64 v5, v5, v8, s[4:5]
	v_rsq_f32_e32 v5, v5
	s_nop 0
	v_mul_f32_e32 v8, 0x45800000, v5
	v_cndmask_b32_e64 v5, v5, v8, s[4:5]
	v_mul_f32_e32 v5, v12, v5
	v_fma_f32 v5, v181, v5, v184
	v_fmac_f32_e32 v5, s42, v39
	s_waitcnt lgkmcnt(0)
	v_mul_f32_e32 v2, v2, v5
	v_cvt_pk_bf16_f32 v2, v2, s0
	global_store_short v[6:7], v2, off
	v_mul_f32_e32 v2, 0x4b800000, v4
	v_cndmask_b32_e32 v2, v4, v2, vcc
	v_rsq_f32_e32 v2, v2
	v_ashrrev_i32_e32 v39, 31, v38
	v_add_f32_dpp v8, v157, v157 quad_perm:[1,0,3,2] row_mask:0xf bank_mask:0xf bound_ctrl:1
	v_lshlrev_b64 v[6:7], 11, v[36:37]
	v_mul_f32_e32 v4, 0x45800000, v2
	v_cndmask_b32_e32 v2, v2, v4, vcc
	v_mul_f32_e32 v2, v159, v2
	v_fma_f32 v2, v181, v2, v184
	v_fmac_f32_e32 v2, s43, v44
	v_mul_f32_e32 v2, v3, v2
	v_cvt_pk_bf16_f32 v4, v2, s0
	v_lshlrev_b64 v[2:3], 11, v[38:39]
	v_lshl_add_u64 v[2:3], v[144:145], 0, v[2:3]
	global_store_short v[2:3], v4, off
	v_add_f32_dpp v4, v156, v156 quad_perm:[1,0,3,2] row_mask:0xf bank_mask:0xf bound_ctrl:1
	v_add_f32_dpp v8, v8, v8 quad_perm:[2,3,0,1] row_mask:0xf bank_mask:0xf bound_ctrl:1
	ds_read2st64_b32 v[2:3], v202 offset0:12 offset1:13
	v_add_f32_dpp v4, v4, v4 quad_perm:[2,3,0,1] row_mask:0xf bank_mask:0xf bound_ctrl:1
	v_add_f32_dpp v8, v8, v8 row_ror:4 row_mask:0xf bank_mask:0xf bound_ctrl:1
	v_lshl_add_u64 v[6:7], v[144:145], 0, v[6:7]
	v_add_f32_dpp v4, v4, v4 row_ror:4 row_mask:0xf bank_mask:0xf bound_ctrl:1
	v_add_f32_dpp v8, v8, v8 row_ror:8 row_mask:0xf bank_mask:0xf bound_ctrl:1
	s_nop 0
	v_add_f32_dpp v4, v4, v4 row_ror:8 row_mask:0xf bank_mask:0xf bound_ctrl:1
	v_readlane_b32 s43, v8, 48
	v_readlane_b32 s3, v4, 16
	v_readlane_b32 s42, v4, 48
	v_readlane_b32 s4, v4, 0
	v_readlane_b32 s5, v4, 32
	v_mov_b32_e32 v4, s3
	v_mov_b32_e32 v5, s42
	v_pk_add_f32 v[4:5], s[4:5], v[4:5]
	v_mov_b32_e32 v9, s43
	v_add_f32_e32 v4, v4, v5
	v_fmamk_f32 v12, v4, 0xbc800000, v156
	v_mul_f32_e32 v4, v12, v12
	v_mov_b32_e32 v5, v197
	s_nop 1
	v_mov_b32_dpp v5, v4 quad_perm:[1,0,3,2] row_mask:0xf bank_mask:0xf
	v_fmac_f32_e32 v5, v12, v12
	s_nop 1
	v_add_f32_dpp v4, v5, v5 quad_perm:[2,3,0,1] row_mask:0xf bank_mask:0xf bound_ctrl:1
	s_nop 1
	v_add_f32_dpp v4, v4, v4 row_ror:4 row_mask:0xf bank_mask:0xf bound_ctrl:1
	s_nop 1
	v_add_f32_dpp v4, v4, v4 row_ror:8 row_mask:0xf bank_mask:0xf bound_ctrl:1
	s_nop 0
	v_readlane_b32 s3, v4, 16
	v_readlane_b32 s42, v4, 48
	v_readlane_b32 s4, v4, 0
	v_readlane_b32 s5, v4, 32
	v_mov_b32_e32 v4, s3
	v_mov_b32_e32 v5, s42
	v_readlane_b32 s42, v8, 16
	v_pk_add_f32 v[4:5], s[4:5], v[4:5]
	v_readlane_b32 s4, v8, 0
	v_readlane_b32 s5, v8, 32
	v_mov_b32_e32 v8, s42
	v_mov_b32_e32 v11, v4
	v_pk_add_f32 v[8:9], s[4:5], v[8:9]
	v_readlane_b32 s3, v33, 13
	v_add_f32_e32 v8, v8, v9
	v_fmac_f32_e32 v157, 0xbc800000, v8
	v_mul_f32_e32 v8, v157, v157
	v_mov_b32_e32 v9, v197
	s_nop 1
	v_mov_b32_dpp v9, v8 quad_perm:[1,0,3,2] row_mask:0xf bank_mask:0xf
	v_fmac_f32_e32 v9, v157, v157
	s_nop 1
	v_add_f32_dpp v8, v9, v9 quad_perm:[2,3,0,1] row_mask:0xf bank_mask:0xf bound_ctrl:1
	s_nop 1
	v_add_f32_dpp v8, v8, v8 row_ror:4 row_mask:0xf bank_mask:0xf bound_ctrl:1
	s_nop 1
	v_add_f32_dpp v8, v8, v8 row_ror:8 row_mask:0xf bank_mask:0xf bound_ctrl:1
	s_nop 0
	v_readlane_b32 s42, v8, 16
	v_readlane_b32 s43, v8, 48
	v_readlane_b32 s4, v8, 0
	v_readlane_b32 s5, v8, 32
	v_mov_b32_e32 v8, s42
	v_mov_b32_e32 v9, s43
	v_pk_add_f32 v[8:9], s[4:5], v[8:9]
	s_nop 0
	v_mov_b32_e32 v10, v8
	v_mov_b32_e32 v4, v9
	v_pk_add_f32 v[4:5], v[10:11], v[4:5]
	s_nop 0
	v_pk_fma_f32 v[4:5], v[4:5], s[52:53], v[0:1] op_sel_hi:[1,0,0]
	s_nop 0
	v_mul_f32_e32 v8, 0x4b800000, v5
	v_cmp_gt_f32_e64 s[4:5], s69, v5
	v_cmp_gt_f32_e32 vcc, s69, v4
	s_nop 0
	v_cndmask_b32_e64 v5, v5, v8, s[4:5]
	v_rsq_f32_e32 v5, v5
	s_nop 0
	v_mul_f32_e32 v8, 0x45800000, v5
	v_cndmask_b32_e64 v5, v5, v8, s[4:5]
	v_mul_f32_e32 v5, v12, v5
	v_fma_f32 v5, v181, v5, v184
	v_fmac_f32_e32 v5, s2, v41
	s_waitcnt lgkmcnt(0)
	v_mul_f32_e32 v2, v2, v5
	v_cvt_pk_bf16_f32 v2, v2, s0
	global_store_short v[6:7], v2, off
	v_mul_f32_e32 v2, 0x4b800000, v4
	v_cndmask_b32_e32 v2, v4, v2, vcc
	v_rsq_f32_e32 v2, v2
	v_ashrrev_i32_e32 v41, 31, v40
	v_add_f32_dpp v8, v155, v155 quad_perm:[1,0,3,2] row_mask:0xf bank_mask:0xf bound_ctrl:1
	v_readlane_b32 s2, v33, 14
	v_mul_f32_e32 v4, 0x45800000, v2
	v_cndmask_b32_e32 v2, v2, v4, vcc
	v_mul_f32_e32 v2, v157, v2
	v_fma_f32 v2, v181, v2, v184
	v_fmac_f32_e32 v2, s3, v45
	v_mul_f32_e32 v2, v3, v2
	v_cvt_pk_bf16_f32 v4, v2, s0
	v_lshlrev_b64 v[2:3], 11, v[40:41]
	v_lshl_add_u64 v[2:3], v[144:145], 0, v[2:3]
	global_store_short v[2:3], v4, off
	v_add_f32_dpp v4, v154, v154 quad_perm:[1,0,3,2] row_mask:0xf bank_mask:0xf bound_ctrl:1
	v_add_f32_dpp v8, v8, v8 quad_perm:[2,3,0,1] row_mask:0xf bank_mask:0xf bound_ctrl:1
	ds_read2st64_b32 v[2:3], v202 offset0:14 offset1:15
	v_add_f32_dpp v4, v4, v4 quad_perm:[2,3,0,1] row_mask:0xf bank_mask:0xf bound_ctrl:1
	v_add_f32_dpp v8, v8, v8 row_ror:4 row_mask:0xf bank_mask:0xf bound_ctrl:1
	v_lshlrev_b64 v[6:7], 11, v[26:27]
	v_add_f32_dpp v4, v4, v4 row_ror:4 row_mask:0xf bank_mask:0xf bound_ctrl:1
	v_add_f32_dpp v8, v8, v8 row_ror:8 row_mask:0xf bank_mask:0xf bound_ctrl:1
	v_lshl_add_u64 v[6:7], v[144:145], 0, v[6:7]
	v_add_f32_dpp v4, v4, v4 row_ror:8 row_mask:0xf bank_mask:0xf bound_ctrl:1
	v_readlane_b32 s43, v8, 48
	v_readlane_b32 s3, v4, 16
	v_readlane_b32 s42, v4, 48
	v_readlane_b32 s4, v4, 0
	v_readlane_b32 s5, v4, 32
	v_mov_b32_e32 v4, s3
	v_mov_b32_e32 v5, s42
	v_pk_add_f32 v[4:5], s[4:5], v[4:5]
	v_mov_b32_e32 v9, s43
	v_add_f32_e32 v4, v4, v5
	v_fmamk_f32 v12, v4, 0xbc800000, v154
	v_mul_f32_e32 v4, v12, v12
	v_mov_b32_e32 v5, v197
	s_nop 1
	v_mov_b32_dpp v5, v4 quad_perm:[1,0,3,2] row_mask:0xf bank_mask:0xf
	v_fmac_f32_e32 v5, v12, v12
	s_nop 1
	v_add_f32_dpp v4, v5, v5 quad_perm:[2,3,0,1] row_mask:0xf bank_mask:0xf bound_ctrl:1
	s_nop 1
	v_add_f32_dpp v4, v4, v4 row_ror:4 row_mask:0xf bank_mask:0xf bound_ctrl:1
	s_nop 1
	v_add_f32_dpp v4, v4, v4 row_ror:8 row_mask:0xf bank_mask:0xf bound_ctrl:1
	s_nop 0
	v_readlane_b32 s3, v4, 16
	v_readlane_b32 s42, v4, 48
	v_readlane_b32 s4, v4, 0
	v_readlane_b32 s5, v4, 32
	v_mov_b32_e32 v4, s3
	v_mov_b32_e32 v5, s42
	v_readlane_b32 s42, v8, 16
	v_pk_add_f32 v[4:5], s[4:5], v[4:5]
	v_readlane_b32 s4, v8, 0
	v_readlane_b32 s5, v8, 32
	v_mov_b32_e32 v8, s42
	v_mov_b32_e32 v11, v4
	v_pk_add_f32 v[8:9], s[4:5], v[8:9]
	v_readlane_b32 s3, v33, 15
	v_add_f32_e32 v8, v8, v9
	v_fmac_f32_e32 v155, 0xbc800000, v8
	v_mul_f32_e32 v8, v155, v155
	v_mov_b32_e32 v9, v197
	v_ashrrev_i32_e32 v33, 31, v32
	s_nop 0
	v_mov_b32_dpp v9, v8 quad_perm:[1,0,3,2] row_mask:0xf bank_mask:0xf
	v_fmac_f32_e32 v9, v155, v155
	s_nop 1
	v_add_f32_dpp v8, v9, v9 quad_perm:[2,3,0,1] row_mask:0xf bank_mask:0xf bound_ctrl:1
	s_nop 1
	v_add_f32_dpp v8, v8, v8 row_ror:4 row_mask:0xf bank_mask:0xf bound_ctrl:1
	s_nop 1
	v_add_f32_dpp v8, v8, v8 row_ror:8 row_mask:0xf bank_mask:0xf bound_ctrl:1
	s_nop 0
	v_readlane_b32 s42, v8, 16
	v_readlane_b32 s43, v8, 48
	v_readlane_b32 s4, v8, 0
	v_readlane_b32 s5, v8, 32
	v_mov_b32_e32 v8, s42
	v_mov_b32_e32 v9, s43
	v_pk_add_f32 v[8:9], s[4:5], v[8:9]
	s_nop 0
	v_mov_b32_e32 v10, v8
	v_mov_b32_e32 v4, v9
	v_pk_add_f32 v[4:5], v[10:11], v[4:5]
	s_nop 0
	v_pk_fma_f32 v[0:1], v[4:5], s[52:53], v[0:1] op_sel_hi:[1,0,0]
	s_nop 0
	v_mul_f32_e32 v4, 0x4b800000, v1
	v_cmp_gt_f32_e64 s[4:5], s69, v1
	v_cmp_gt_f32_e32 vcc, s69, v0
	s_nop 0
	v_cndmask_b32_e64 v1, v1, v4, s[4:5]
	v_rsq_f32_e32 v1, v1
	s_nop 0
	v_mul_f32_e32 v4, 0x45800000, v1
	v_cndmask_b32_e64 v1, v1, v4, s[4:5]
	v_mul_f32_e32 v1, v12, v1
	v_fma_f32 v1, v181, v1, v184
	v_fmac_f32_e32 v1, s2, v43
	s_waitcnt lgkmcnt(0)
	v_mul_f32_e32 v1, v2, v1
	v_cvt_pk_bf16_f32 v1, v1, s0
	global_store_short v[6:7], v1, off
	v_mul_f32_e32 v1, 0x4b800000, v0
	v_cndmask_b32_e32 v0, v0, v1, vcc
	v_rsq_f32_e32 v0, v0
	s_mov_b64 s[4:5], 0
	v_mul_f32_e32 v1, 0x45800000, v0
	v_cndmask_b32_e32 v0, v0, v1, vcc
	v_mul_f32_e32 v0, v155, v0
	v_fma_f32 v0, v181, v0, v184
	v_fmac_f32_e32 v0, s3, v42
	v_mul_f32_e32 v0, v3, v0
	v_cvt_pk_bf16_f32 v2, v0, s0
	v_lshlrev_b64 v[0:1], 11, v[32:33]
	v_lshl_add_u64 v[0:1], v[144:145], 0, v[0:1]
	s_andn2_b64 vcc, exec, s[40:41]
	global_store_short v[0:1], v2, off
	s_cbranch_vccz .LBB0_631
